# plus: ret_step2 gate loads prefetched and loop unrolled; GEMM closing barrier moved into the skinny unit before its first LDS write (out, up phases)
# speedup vs baseline: 1.0267x; 1.0011x over previous
; #define LAS __attribute__((address_space(3)))
; DI unsigned pk2(float lo, float hi) { f32x2 v = {lo, hi}; return __builtin_bit_cast(unsigned, __builtin_convertvector(v, bf16x2v)); }
; DI float bflo(unsigned u) { return __uint_as_float(u << 16); }
; DI float bfhi(unsigned u) { return __uint_as_float(u & 0xffff0000u); }
; DI float silu_f(float x) { return x * __builtin_amdgcn_rcpf(1.0f + __builtin_amdgcn_exp2f(-1.4426950408889634f * x)); }
; DI void ret_step2(LAS unsigned char* lds, const bf16_t* Z, const bf16_t* SP, bf16_t* MIX, const float* rng, int n, int h, int tid) {
;     ...
;     const float rstd = rsqrtf((red[wid * 32 + r] + red[(wid ^ 1) * 32 + r]) * (1.0f / 256.0f) + EPS);
; #pragma unroll
;     for (int dt = 0; dt < 4; ++dt)
; #pragma unroll
;         for (int g4 = 0; g4 < 4; ++g4) { const int dv = 128 * dh + 32 * dt + 8 * g4 + 4 * hh;
;             *(LAS f32x4*)(lds + (32 * it_ + r) * 1040 + dv * 4) = (f32x4){acc[dt][4 * g4] * rstd, acc[dt][4 * g4 + 1] * rstd, acc[dt][4 * g4 + 2] * rstd, acc[dt][4 * g4 + 3] * rstd}; }
;     __syncthreads();
; #pragma unroll 1
;     for (int k = 0; k < 8; ++k) {
;         const int it = k * 512 + tid, tk = it >> 5, c8 = (it & 31) * 8; const size_t token = (size_t)n * 128 + tk;
;         const u32x4 gz = *(const u32x4*)(Z + token * INW + C_RG + h * 256 + c8);
;         const f32x4 g0 = *(const f32x4*)(rng + h * 256 + c8), g1 = *(const f32x4*)(rng + h * 256 + c8 + 4);
;         const f32x4 p0 = *(const LAS f32x4*)(lds + tk * 1040 + c8 * 4), p1 = *(const LAS f32x4*)(lds + tk * 1040 + c8 * 4 + 16);
;         u32x4 o;
;         o.x = pk2(p0[0] * g0[0] * silu_f(bflo(gz.x)), p0[1] * g0[1] * silu_f(bfhi(gz.x))); o.y = pk2(p0[2] * g0[2] * silu_f(bflo(gz.y)), p0[3] * g0[3] * silu_f(bfhi(gz.y)));
;         o.z = pk2(p1[0] * g1[0] * silu_f(bflo(gz.z)), p1[1] * g1[1] * silu_f(bfhi(gz.z))); o.w = pk2(p1[2] * g1[2] * silu_f(bflo(gz.w)), p1[3] * g1[3] * silu_f(bfhi(gz.w)));
;         *(u32x4*)(MIX + token * DM + 1024 + h * 256 + c8) = o;
;     }
.LBB0_416:
	s_or_b64 exec, exec, s[2:3]
	s_waitcnt lgkmcnt(0)
	s_barrier
	ds_read_b32 v65, v218
	ds_read_b32 v66, v219
	s_mov_b32 s3, 0x800000
	s_and_b32 s2, s75, 3
	s_ashr_i32 s53, s52, 31
	s_lshl_b32 s2, s2, 9
	s_waitcnt lgkmcnt(0)
	v_add_f32_e32 v65, v65, v66
	v_fmamk_f32 v65, v65, 0x3b800000, v249
	v_cmp_gt_f32_e32 vcc, s3, v65
	v_mul_f32_e32 v66, 0x4b800000, v65
	s_lshl_b32 s42, s40, 2
	v_cndmask_b32_e32 v65, v65, v66, vcc
	v_rsq_f32_e32 v65, v65
	s_lshl_b64 s[40:41], s[52:53], 19
	s_or_b32 s40, s40, s2
	s_mul_hi_i32 s3, s52, 0x150000
	v_mul_f32_e32 v66, 0x45800000, v65
	v_cndmask_b32_e32 v66, v65, v66, vcc
	v_pk_mul_f32 v[0:1], v[0:1], v[66:67] op_sel_hi:[1,0]
	v_pk_mul_f32 v[2:3], v[2:3], v[66:67] op_sel_hi:[1,0]
	v_pk_mul_f32 v[48:49], v[48:49], v[66:67] op_sel_hi:[1,0]
	v_pk_mul_f32 v[50:51], v[50:51], v[66:67] op_sel_hi:[1,0]
	v_pk_mul_f32 v[32:33], v[32:33], v[66:67] op_sel_hi:[1,0]
	v_pk_mul_f32 v[34:35], v[34:35], v[66:67] op_sel_hi:[1,0]
	v_pk_mul_f32 v[16:17], v[16:17], v[66:67] op_sel_hi:[1,0]
	v_pk_mul_f32 v[18:19], v[18:19], v[66:67] op_sel_hi:[1,0]
	ds_write_b128 v250, v[0:3] offset:384
	v_pk_mul_f32 v[0:1], v[4:5], v[66:67] op_sel_hi:[1,0]
	v_pk_mul_f32 v[2:3], v[6:7], v[66:67] op_sel_hi:[1,0]
	ds_write_b128 v250, v[48:51]
	v_pk_mul_f32 v[48:49], v[52:53], v[66:67] op_sel_hi:[1,0]
	v_pk_mul_f32 v[50:51], v[54:55], v[66:67] op_sel_hi:[1,0]
	ds_write_b128 v250, v[32:35] offset:128
	v_pk_mul_f32 v[32:33], v[36:37], v[66:67] op_sel_hi:[1,0]
	v_pk_mul_f32 v[34:35], v[38:39], v[66:67] op_sel_hi:[1,0]
	ds_write_b128 v250, v[16:19] offset:256
	v_pk_mul_f32 v[16:17], v[20:21], v[66:67] op_sel_hi:[1,0]
	v_pk_mul_f32 v[18:19], v[22:23], v[66:67] op_sel_hi:[1,0]
	ds_write_b128 v250, v[0:3] offset:416
	v_pk_mul_f32 v[0:1], v[8:9], v[66:67] op_sel_hi:[1,0]
	v_pk_mul_f32 v[2:3], v[10:11], v[66:67] op_sel_hi:[1,0]
	ds_write_b128 v250, v[48:51] offset:32
	v_pk_mul_f32 v[48:49], v[56:57], v[66:67] op_sel_hi:[1,0]
	v_pk_mul_f32 v[50:51], v[58:59], v[66:67] op_sel_hi:[1,0]
	ds_write_b128 v250, v[32:35] offset:160
	v_pk_mul_f32 v[32:33], v[40:41], v[66:67] op_sel_hi:[1,0]
	v_pk_mul_f32 v[34:35], v[42:43], v[66:67] op_sel_hi:[1,0]
	ds_write_b128 v250, v[16:19] offset:288
	v_pk_mul_f32 v[16:17], v[24:25], v[66:67] op_sel_hi:[1,0]
	v_pk_mul_f32 v[18:19], v[26:27], v[66:67] op_sel_hi:[1,0]
	ds_write_b128 v250, v[0:3] offset:448
	v_pk_mul_f32 v[0:1], v[12:13], v[66:67] op_sel_hi:[1,0]
	v_pk_mul_f32 v[2:3], v[14:15], v[66:67] op_sel_hi:[1,0]
	s_or_b32 s2, s77, s2
	ds_write_b128 v250, v[48:51] offset:64
	v_pk_mul_f32 v[48:49], v[60:61], v[66:67] op_sel_hi:[1,0]
	v_pk_mul_f32 v[50:51], v[62:63], v[66:67] op_sel_hi:[1,0]
	ds_write_b128 v250, v[32:35] offset:192
	v_pk_mul_f32 v[32:33], v[44:45], v[66:67] op_sel_hi:[1,0]
	v_pk_mul_f32 v[34:35], v[46:47], v[66:67] op_sel_hi:[1,0]
	ds_write_b128 v250, v[16:19] offset:320
	v_pk_mul_f32 v[16:17], v[28:29], v[66:67] op_sel_hi:[1,0]
	v_pk_mul_f32 v[18:19], v[30:31], v[66:67] op_sel_hi:[1,0]
	ds_write_b128 v250, v[0:3] offset:480
	v_lshl_add_u64 v[0:1], v[160:161], 0, s[42:43]
	v_lshl_add_u64 v[2:3], v[168:169], 0, s[40:41]
	v_lshl_add_u64 v[4:5], v[170:171], 0, s[2:3]
	s_mov_b32 s2, 0
	ds_write_b128 v250, v[48:51] offset:96
	ds_write_b128 v250, v[32:35] offset:224
	ds_write_b128 v250, v[16:19] offset:352
	s_mov_b64 s[40:41], 0x2a000
	global_load_dwordx4 v[72:75], v[0:1], off
	global_load_dwordx4 v[76:79], v[0:1], off offset:16
	global_load_dwordx4 v[80:83], v[4:5], off
	v_lshl_add_u64 v[4:5], v[4:5], 0, s[40:41]
	global_load_dwordx4 v[84:87], v[4:5], off
	v_lshl_add_u64 v[4:5], v[4:5], 0, s[40:41]
	global_load_dwordx4 v[88:91], v[4:5], off
	v_lshl_add_u64 v[4:5], v[4:5], 0, s[40:41]
	global_load_dwordx4 v[92:95], v[4:5], off
	v_lshl_add_u64 v[4:5], v[4:5], 0, s[40:41]
	global_load_dwordx4 v[96:99], v[4:5], off
	v_lshl_add_u64 v[4:5], v[4:5], 0, s[40:41]
	global_load_dwordx4 v[100:103], v[4:5], off
	v_lshl_add_u64 v[4:5], v[4:5], 0, s[40:41]
	global_load_dwordx4 v[104:107], v[4:5], off
	v_lshl_add_u64 v[4:5], v[4:5], 0, s[40:41]
	global_load_dwordx4 v[108:111], v[4:5], off
	s_mov_b64 s[40:41], 0x10000
	s_waitcnt lgkmcnt(0)
	s_barrier
.LBB0_417:
	v_mov_b32_e32 v22, v223
	ds_read_b128 v[18:21], v22
	ds_read_b128 v[22:25], v22 offset:16
	s_waitcnt vmcnt(7)
	v_lshlrev_b32_e32 v26, 16, v80
	v_and_b32_e32 v27, 0xffff0000, v80
	v_lshlrev_b32_e32 v28, 16, v81
	v_and_b32_e32 v29, 0xffff0000, v81
	v_lshlrev_b32_e32 v30, 16, v82
	v_and_b32_e32 v31, 0xffff0000, v82
	v_lshlrev_b32_e32 v32, 16, v83
	v_and_b32_e32 v33, 0xffff0000, v83
	v_mul_f32_e32 v34, 0xbfb8aa3b, v26
	v_mul_f32_e32 v35, 0xbfb8aa3b, v27
	v_mul_f32_e32 v36, 0xbfb8aa3b, v28
	v_mul_f32_e32 v37, 0xbfb8aa3b, v29
	v_mul_f32_e32 v38, 0xbfb8aa3b, v30
	v_mul_f32_e32 v39, 0xbfb8aa3b, v31
	v_mul_f32_e32 v40, 0xbfb8aa3b, v32
	v_mul_f32_e32 v41, 0xbfb8aa3b, v33
	v_exp_f32_e32 v34, v34
	v_exp_f32_e32 v35, v35
	v_exp_f32_e32 v36, v36
	v_exp_f32_e32 v37, v37
	v_exp_f32_e32 v38, v38
	v_exp_f32_e32 v39, v39
	v_exp_f32_e32 v40, v40
	v_exp_f32_e32 v41, v41
	v_add_f32_e32 v34, 1.0, v34
	v_add_f32_e32 v35, 1.0, v35
	v_add_f32_e32 v36, 1.0, v36
	v_add_f32_e32 v37, 1.0, v37
	v_add_f32_e32 v38, 1.0, v38
	v_add_f32_e32 v39, 1.0, v39
	v_add_f32_e32 v40, 1.0, v40
	v_add_f32_e32 v41, 1.0, v41
	v_rcp_f32_e32 v34, v34
	v_rcp_f32_e32 v35, v35
	v_rcp_f32_e32 v36, v36
	v_rcp_f32_e32 v37, v37
	v_rcp_f32_e32 v38, v38
	v_rcp_f32_e32 v39, v39
	v_rcp_f32_e32 v40, v40
	v_rcp_f32_e32 v41, v41
	s_waitcnt lgkmcnt(0)
; #define LAS __attribute__((address_space(3)))
; DI unsigned pk2(float lo, float hi) { f32x2 v = {lo, hi}; return __builtin_bit_cast(unsigned, __builtin_convertvector(v, bf16x2v)); }
; DI float bflo(unsigned u) { return __uint_as_float(u << 16); }
; DI float bfhi(unsigned u) { return __uint_as_float(u & 0xffff0000u); }
; DI float silu_f(float x) { return x * __builtin_amdgcn_rcpf(1.0f + __builtin_amdgcn_exp2f(-1.4426950408889634f * x)); }
; DI void ret_step2(LAS unsigned char* lds, const bf16_t* Z, const bf16_t* SP, bf16_t* MIX, const float* rng, int n, int h, int tid) {
;     ...
;         const int it = k * 512 + tid, tk = it >> 5, c8 = (it & 31) * 8; const size_t token = (size_t)n * 128 + tk;
;         const u32x4 gz = *(const u32x4*)(Z + token * INW + C_RG + h * 256 + c8);
;         const f32x4 g0 = *(const f32x4*)(rng + h * 256 + c8), g1 = *(const f32x4*)(rng + h * 256 + c8 + 4);
;         const f32x4 p0 = *(const LAS f32x4*)(lds + tk * 1040 + c8 * 4), p1 = *(const LAS f32x4*)(lds + tk * 1040 + c8 * 4 + 16);
;         u32x4 o;
;         o.x = pk2(p0[0] * g0[0] * silu_f(bflo(gz.x)), p0[1] * g0[1] * silu_f(bfhi(gz.x))); o.y = pk2(p0[2] * g0[2] * silu_f(bflo(gz.y)), p0[3] * g0[3] * silu_f(bfhi(gz.y)));
;         o.z = pk2(p1[0] * g1[0] * silu_f(bflo(gz.z)), p1[1] * g1[1] * silu_f(bfhi(gz.z))); o.w = pk2(p1[2] * g1[2] * silu_f(bflo(gz.w)), p1[3] * g1[3] * silu_f(bfhi(gz.w)));
;         *(u32x4*)(MIX + token * DM + 1024 + h * 256 + c8) = o;
	v_pk_mul_f32 v[10:11], v[72:73], v[18:19]
	v_pk_mul_f32 v[12:13], v[74:75], v[20:21]
	v_pk_mul_f32 v[14:15], v[76:77], v[22:23]
	v_pk_mul_f32 v[16:17], v[78:79], v[24:25]
	v_pk_mul_f32 v[34:35], v[34:35], v[26:27]
	v_pk_mul_f32 v[36:37], v[36:37], v[28:29]
	v_pk_mul_f32 v[38:39], v[38:39], v[30:31]
	v_pk_mul_f32 v[40:41], v[40:41], v[32:33]
	v_pk_mul_f32 v[10:11], v[10:11], v[34:35]
	v_pk_mul_f32 v[12:13], v[12:13], v[36:37]
	v_pk_mul_f32 v[14:15], v[14:15], v[38:39]
	v_pk_mul_f32 v[16:17], v[16:17], v[40:41]
	v_cvt_pk_bf16_f32 v6, v10, v11
	v_cvt_pk_bf16_f32 v7, v12, v13
	v_cvt_pk_bf16_f32 v8, v14, v15
	v_cvt_pk_bf16_f32 v9, v16, v17
	global_store_dwordx4 v[2:3], v[6:9], off
	v_lshl_add_u64 v[2:3], v[2:3], 0, s[40:41]
	v_add_u32_e32 v22, 0x4100, v223
	ds_read_b128 v[18:21], v22
	ds_read_b128 v[22:25], v22 offset:16
	s_waitcnt vmcnt(7)
	v_lshlrev_b32_e32 v26, 16, v84
	v_and_b32_e32 v27, 0xffff0000, v84
	v_lshlrev_b32_e32 v28, 16, v85
	v_and_b32_e32 v29, 0xffff0000, v85
	v_lshlrev_b32_e32 v30, 16, v86
	v_and_b32_e32 v31, 0xffff0000, v86
	v_lshlrev_b32_e32 v32, 16, v87
	v_and_b32_e32 v33, 0xffff0000, v87
	v_mul_f32_e32 v34, 0xbfb8aa3b, v26
	v_mul_f32_e32 v35, 0xbfb8aa3b, v27
	v_mul_f32_e32 v36, 0xbfb8aa3b, v28
	v_mul_f32_e32 v37, 0xbfb8aa3b, v29
	v_mul_f32_e32 v38, 0xbfb8aa3b, v30
	v_mul_f32_e32 v39, 0xbfb8aa3b, v31
	v_mul_f32_e32 v40, 0xbfb8aa3b, v32
	v_mul_f32_e32 v41, 0xbfb8aa3b, v33
	v_exp_f32_e32 v34, v34
	v_exp_f32_e32 v35, v35
	v_exp_f32_e32 v36, v36
	v_exp_f32_e32 v37, v37
	v_exp_f32_e32 v38, v38
	v_exp_f32_e32 v39, v39
	v_exp_f32_e32 v40, v40
	v_exp_f32_e32 v41, v41
	v_add_f32_e32 v34, 1.0, v34
	v_add_f32_e32 v35, 1.0, v35
	v_add_f32_e32 v36, 1.0, v36
	v_add_f32_e32 v37, 1.0, v37
	v_add_f32_e32 v38, 1.0, v38
	v_add_f32_e32 v39, 1.0, v39
	v_add_f32_e32 v40, 1.0, v40
	v_add_f32_e32 v41, 1.0, v41
	v_rcp_f32_e32 v34, v34
	v_rcp_f32_e32 v35, v35
	v_rcp_f32_e32 v36, v36
	v_rcp_f32_e32 v37, v37
	v_rcp_f32_e32 v38, v38
	v_rcp_f32_e32 v39, v39
	v_rcp_f32_e32 v40, v40
	v_rcp_f32_e32 v41, v41
	s_waitcnt lgkmcnt(0)
	v_pk_mul_f32 v[10:11], v[72:73], v[18:19]
	v_pk_mul_f32 v[12:13], v[74:75], v[20:21]
	v_pk_mul_f32 v[14:15], v[76:77], v[22:23]
	v_pk_mul_f32 v[16:17], v[78:79], v[24:25]
	v_pk_mul_f32 v[34:35], v[34:35], v[26:27]
	v_pk_mul_f32 v[36:37], v[36:37], v[28:29]
	v_pk_mul_f32 v[38:39], v[38:39], v[30:31]
	v_pk_mul_f32 v[40:41], v[40:41], v[32:33]
	v_pk_mul_f32 v[10:11], v[10:11], v[34:35]
	v_pk_mul_f32 v[12:13], v[12:13], v[36:37]
	v_pk_mul_f32 v[14:15], v[14:15], v[38:39]
	v_pk_mul_f32 v[16:17], v[16:17], v[40:41]
	v_cvt_pk_bf16_f32 v6, v10, v11
	v_cvt_pk_bf16_f32 v7, v12, v13
	v_cvt_pk_bf16_f32 v8, v14, v15
	v_cvt_pk_bf16_f32 v9, v16, v17
	global_store_dwordx4 v[2:3], v[6:9], off
	v_lshl_add_u64 v[2:3], v[2:3], 0, s[40:41]
	v_add_u32_e32 v22, 0x8200, v223
	ds_read_b128 v[18:21], v22
	ds_read_b128 v[22:25], v22 offset:16
	s_waitcnt vmcnt(7)
	v_lshlrev_b32_e32 v26, 16, v88
	v_and_b32_e32 v27, 0xffff0000, v88
	v_lshlrev_b32_e32 v28, 16, v89
	v_and_b32_e32 v29, 0xffff0000, v89
	v_lshlrev_b32_e32 v30, 16, v90
	v_and_b32_e32 v31, 0xffff0000, v90
	v_lshlrev_b32_e32 v32, 16, v91
	v_and_b32_e32 v33, 0xffff0000, v91
	v_mul_f32_e32 v34, 0xbfb8aa3b, v26
	v_mul_f32_e32 v35, 0xbfb8aa3b, v27
	v_mul_f32_e32 v36, 0xbfb8aa3b, v28
	v_mul_f32_e32 v37, 0xbfb8aa3b, v29
	v_mul_f32_e32 v38, 0xbfb8aa3b, v30
	v_mul_f32_e32 v39, 0xbfb8aa3b, v31
	v_mul_f32_e32 v40, 0xbfb8aa3b, v32
	v_mul_f32_e32 v41, 0xbfb8aa3b, v33
	v_exp_f32_e32 v34, v34
	v_exp_f32_e32 v35, v35
	v_exp_f32_e32 v36, v36
	v_exp_f32_e32 v37, v37
	v_exp_f32_e32 v38, v38
	v_exp_f32_e32 v39, v39
	v_exp_f32_e32 v40, v40
	v_exp_f32_e32 v41, v41
	v_add_f32_e32 v34, 1.0, v34
	v_add_f32_e32 v35, 1.0, v35
	v_add_f32_e32 v36, 1.0, v36
	v_add_f32_e32 v37, 1.0, v37
	v_add_f32_e32 v38, 1.0, v38
	v_add_f32_e32 v39, 1.0, v39
	v_add_f32_e32 v40, 1.0, v40
	v_add_f32_e32 v41, 1.0, v41
	v_rcp_f32_e32 v34, v34
	v_rcp_f32_e32 v35, v35
	v_rcp_f32_e32 v36, v36
	v_rcp_f32_e32 v37, v37
	v_rcp_f32_e32 v38, v38
	v_rcp_f32_e32 v39, v39
	v_rcp_f32_e32 v40, v40
	v_rcp_f32_e32 v41, v41
	s_waitcnt lgkmcnt(0)
	v_pk_mul_f32 v[10:11], v[72:73], v[18:19]
	v_pk_mul_f32 v[12:13], v[74:75], v[20:21]
	v_pk_mul_f32 v[14:15], v[76:77], v[22:23]
	v_pk_mul_f32 v[16:17], v[78:79], v[24:25]
	v_pk_mul_f32 v[34:35], v[34:35], v[26:27]
	v_pk_mul_f32 v[36:37], v[36:37], v[28:29]
	v_pk_mul_f32 v[38:39], v[38:39], v[30:31]
	v_pk_mul_f32 v[40:41], v[40:41], v[32:33]
	v_pk_mul_f32 v[10:11], v[10:11], v[34:35]
	v_pk_mul_f32 v[12:13], v[12:13], v[36:37]
	v_pk_mul_f32 v[14:15], v[14:15], v[38:39]
	v_pk_mul_f32 v[16:17], v[16:17], v[40:41]
	v_cvt_pk_bf16_f32 v6, v10, v11
	v_cvt_pk_bf16_f32 v7, v12, v13
	v_cvt_pk_bf16_f32 v8, v14, v15
	v_cvt_pk_bf16_f32 v9, v16, v17
	global_store_dwordx4 v[2:3], v[6:9], off
	v_lshl_add_u64 v[2:3], v[2:3], 0, s[40:41]
	v_add_u32_e32 v22, 0xc300, v223
	ds_read_b128 v[18:21], v22
	ds_read_b128 v[22:25], v22 offset:16
	s_waitcnt vmcnt(7)
	v_lshlrev_b32_e32 v26, 16, v92
	v_and_b32_e32 v27, 0xffff0000, v92
	v_lshlrev_b32_e32 v28, 16, v93
	v_and_b32_e32 v29, 0xffff0000, v93
	v_lshlrev_b32_e32 v30, 16, v94
	v_and_b32_e32 v31, 0xffff0000, v94
	v_lshlrev_b32_e32 v32, 16, v95
	v_and_b32_e32 v33, 0xffff0000, v95
	v_mul_f32_e32 v34, 0xbfb8aa3b, v26
	v_mul_f32_e32 v35, 0xbfb8aa3b, v27
	v_mul_f32_e32 v36, 0xbfb8aa3b, v28
	v_mul_f32_e32 v37, 0xbfb8aa3b, v29
	v_mul_f32_e32 v38, 0xbfb8aa3b, v30
	v_mul_f32_e32 v39, 0xbfb8aa3b, v31
	v_mul_f32_e32 v40, 0xbfb8aa3b, v32
	v_mul_f32_e32 v41, 0xbfb8aa3b, v33
	v_exp_f32_e32 v34, v34
	v_exp_f32_e32 v35, v35
	v_exp_f32_e32 v36, v36
	v_exp_f32_e32 v37, v37
	v_exp_f32_e32 v38, v38
	v_exp_f32_e32 v39, v39
	v_exp_f32_e32 v40, v40
	v_exp_f32_e32 v41, v41
	v_add_f32_e32 v34, 1.0, v34
	v_add_f32_e32 v35, 1.0, v35
	v_add_f32_e32 v36, 1.0, v36
	v_add_f32_e32 v37, 1.0, v37
	v_add_f32_e32 v38, 1.0, v38
	v_add_f32_e32 v39, 1.0, v39
	v_add_f32_e32 v40, 1.0, v40
	v_add_f32_e32 v41, 1.0, v41
	v_rcp_f32_e32 v34, v34
	v_rcp_f32_e32 v35, v35
	v_rcp_f32_e32 v36, v36
	v_rcp_f32_e32 v37, v37
	v_rcp_f32_e32 v38, v38
	v_rcp_f32_e32 v39, v39
	v_rcp_f32_e32 v40, v40
	v_rcp_f32_e32 v41, v41
	s_waitcnt lgkmcnt(0)
; #define LAS __attribute__((address_space(3)))
; DI unsigned pk2(float lo, float hi) { f32x2 v = {lo, hi}; return __builtin_bit_cast(unsigned, __builtin_convertvector(v, bf16x2v)); }
; DI float bflo(unsigned u) { return __uint_as_float(u << 16); }
; DI float bfhi(unsigned u) { return __uint_as_float(u & 0xffff0000u); }
; DI float silu_f(float x) { return x * __builtin_amdgcn_rcpf(1.0f + __builtin_amdgcn_exp2f(-1.4426950408889634f * x)); }
; DI void ret_step2(LAS unsigned char* lds, const bf16_t* Z, const bf16_t* SP, bf16_t* MIX, const float* rng, int n, int h, int tid) {
;     ...
;         const int it = k * 512 + tid, tk = it >> 5, c8 = (it & 31) * 8; const size_t token = (size_t)n * 128 + tk;
;         const u32x4 gz = *(const u32x4*)(Z + token * INW + C_RG + h * 256 + c8);
;         const f32x4 g0 = *(const f32x4*)(rng + h * 256 + c8), g1 = *(const f32x4*)(rng + h * 256 + c8 + 4);
;         const f32x4 p0 = *(const LAS f32x4*)(lds + tk * 1040 + c8 * 4), p1 = *(const LAS f32x4*)(lds + tk * 1040 + c8 * 4 + 16);
;         u32x4 o;
;         o.x = pk2(p0[0] * g0[0] * silu_f(bflo(gz.x)), p0[1] * g0[1] * silu_f(bfhi(gz.x))); o.y = pk2(p0[2] * g0[2] * silu_f(bflo(gz.y)), p0[3] * g0[3] * silu_f(bfhi(gz.y)));
;         o.z = pk2(p1[0] * g1[0] * silu_f(bflo(gz.z)), p1[1] * g1[1] * silu_f(bfhi(gz.z))); o.w = pk2(p1[2] * g1[2] * silu_f(bflo(gz.w)), p1[3] * g1[3] * silu_f(bfhi(gz.w)));
;         *(u32x4*)(MIX + token * DM + 1024 + h * 256 + c8) = o;
	v_pk_mul_f32 v[10:11], v[72:73], v[18:19]
	v_pk_mul_f32 v[12:13], v[74:75], v[20:21]
	v_pk_mul_f32 v[14:15], v[76:77], v[22:23]
	v_pk_mul_f32 v[16:17], v[78:79], v[24:25]
	v_pk_mul_f32 v[34:35], v[34:35], v[26:27]
	v_pk_mul_f32 v[36:37], v[36:37], v[28:29]
	v_pk_mul_f32 v[38:39], v[38:39], v[30:31]
	v_pk_mul_f32 v[40:41], v[40:41], v[32:33]
	v_pk_mul_f32 v[10:11], v[10:11], v[34:35]
	v_pk_mul_f32 v[12:13], v[12:13], v[36:37]
	v_pk_mul_f32 v[14:15], v[14:15], v[38:39]
	v_pk_mul_f32 v[16:17], v[16:17], v[40:41]
	v_cvt_pk_bf16_f32 v6, v10, v11
	v_cvt_pk_bf16_f32 v7, v12, v13
	v_cvt_pk_bf16_f32 v8, v14, v15
	v_cvt_pk_bf16_f32 v9, v16, v17
	global_store_dwordx4 v[2:3], v[6:9], off
	v_lshl_add_u64 v[2:3], v[2:3], 0, s[40:41]
	v_add_u32_e32 v22, 0x10400, v223
	ds_read_b128 v[18:21], v22
	ds_read_b128 v[22:25], v22 offset:16
	s_waitcnt vmcnt(7)
	v_lshlrev_b32_e32 v26, 16, v96
	v_and_b32_e32 v27, 0xffff0000, v96
	v_lshlrev_b32_e32 v28, 16, v97
	v_and_b32_e32 v29, 0xffff0000, v97
	v_lshlrev_b32_e32 v30, 16, v98
	v_and_b32_e32 v31, 0xffff0000, v98
	v_lshlrev_b32_e32 v32, 16, v99
	v_and_b32_e32 v33, 0xffff0000, v99
	v_mul_f32_e32 v34, 0xbfb8aa3b, v26
	v_mul_f32_e32 v35, 0xbfb8aa3b, v27
	v_mul_f32_e32 v36, 0xbfb8aa3b, v28
	v_mul_f32_e32 v37, 0xbfb8aa3b, v29
	v_mul_f32_e32 v38, 0xbfb8aa3b, v30
	v_mul_f32_e32 v39, 0xbfb8aa3b, v31
	v_mul_f32_e32 v40, 0xbfb8aa3b, v32
	v_mul_f32_e32 v41, 0xbfb8aa3b, v33
	v_exp_f32_e32 v34, v34
	v_exp_f32_e32 v35, v35
	v_exp_f32_e32 v36, v36
	v_exp_f32_e32 v37, v37
	v_exp_f32_e32 v38, v38
	v_exp_f32_e32 v39, v39
	v_exp_f32_e32 v40, v40
	v_exp_f32_e32 v41, v41
	v_add_f32_e32 v34, 1.0, v34
	v_add_f32_e32 v35, 1.0, v35
	v_add_f32_e32 v36, 1.0, v36
	v_add_f32_e32 v37, 1.0, v37
	v_add_f32_e32 v38, 1.0, v38
	v_add_f32_e32 v39, 1.0, v39
	v_add_f32_e32 v40, 1.0, v40
	v_add_f32_e32 v41, 1.0, v41
	v_rcp_f32_e32 v34, v34
	v_rcp_f32_e32 v35, v35
	v_rcp_f32_e32 v36, v36
	v_rcp_f32_e32 v37, v37
	v_rcp_f32_e32 v38, v38
	v_rcp_f32_e32 v39, v39
	v_rcp_f32_e32 v40, v40
	v_rcp_f32_e32 v41, v41
	s_waitcnt lgkmcnt(0)
	v_pk_mul_f32 v[10:11], v[72:73], v[18:19]
	v_pk_mul_f32 v[12:13], v[74:75], v[20:21]
	v_pk_mul_f32 v[14:15], v[76:77], v[22:23]
	v_pk_mul_f32 v[16:17], v[78:79], v[24:25]
	v_pk_mul_f32 v[34:35], v[34:35], v[26:27]
	v_pk_mul_f32 v[36:37], v[36:37], v[28:29]
	v_pk_mul_f32 v[38:39], v[38:39], v[30:31]
	v_pk_mul_f32 v[40:41], v[40:41], v[32:33]
	v_pk_mul_f32 v[10:11], v[10:11], v[34:35]
	v_pk_mul_f32 v[12:13], v[12:13], v[36:37]
	v_pk_mul_f32 v[14:15], v[14:15], v[38:39]
	v_pk_mul_f32 v[16:17], v[16:17], v[40:41]
	v_cvt_pk_bf16_f32 v6, v10, v11
	v_cvt_pk_bf16_f32 v7, v12, v13
	v_cvt_pk_bf16_f32 v8, v14, v15
	v_cvt_pk_bf16_f32 v9, v16, v17
	global_store_dwordx4 v[2:3], v[6:9], off
	v_lshl_add_u64 v[2:3], v[2:3], 0, s[40:41]
	v_add_u32_e32 v22, 0x14500, v223
	ds_read_b128 v[18:21], v22
	ds_read_b128 v[22:25], v22 offset:16
	s_waitcnt vmcnt(7)
	v_lshlrev_b32_e32 v26, 16, v100
	v_and_b32_e32 v27, 0xffff0000, v100
	v_lshlrev_b32_e32 v28, 16, v101
	v_and_b32_e32 v29, 0xffff0000, v101
	v_lshlrev_b32_e32 v30, 16, v102
	v_and_b32_e32 v31, 0xffff0000, v102
	v_lshlrev_b32_e32 v32, 16, v103
	v_and_b32_e32 v33, 0xffff0000, v103
	v_mul_f32_e32 v34, 0xbfb8aa3b, v26
	v_mul_f32_e32 v35, 0xbfb8aa3b, v27
	v_mul_f32_e32 v36, 0xbfb8aa3b, v28
	v_mul_f32_e32 v37, 0xbfb8aa3b, v29
	v_mul_f32_e32 v38, 0xbfb8aa3b, v30
	v_mul_f32_e32 v39, 0xbfb8aa3b, v31
	v_mul_f32_e32 v40, 0xbfb8aa3b, v32
	v_mul_f32_e32 v41, 0xbfb8aa3b, v33
	v_exp_f32_e32 v34, v34
	v_exp_f32_e32 v35, v35
	v_exp_f32_e32 v36, v36
	v_exp_f32_e32 v37, v37
	v_exp_f32_e32 v38, v38
	v_exp_f32_e32 v39, v39
	v_exp_f32_e32 v40, v40
	v_exp_f32_e32 v41, v41
	v_add_f32_e32 v34, 1.0, v34
	v_add_f32_e32 v35, 1.0, v35
	v_add_f32_e32 v36, 1.0, v36
	v_add_f32_e32 v37, 1.0, v37
	v_add_f32_e32 v38, 1.0, v38
	v_add_f32_e32 v39, 1.0, v39
	v_add_f32_e32 v40, 1.0, v40
	v_add_f32_e32 v41, 1.0, v41
	v_rcp_f32_e32 v34, v34
	v_rcp_f32_e32 v35, v35
	v_rcp_f32_e32 v36, v36
	v_rcp_f32_e32 v37, v37
	v_rcp_f32_e32 v38, v38
	v_rcp_f32_e32 v39, v39
	v_rcp_f32_e32 v40, v40
	v_rcp_f32_e32 v41, v41
	s_waitcnt lgkmcnt(0)
	v_pk_mul_f32 v[10:11], v[72:73], v[18:19]
	v_pk_mul_f32 v[12:13], v[74:75], v[20:21]
	v_pk_mul_f32 v[14:15], v[76:77], v[22:23]
	v_pk_mul_f32 v[16:17], v[78:79], v[24:25]
	v_pk_mul_f32 v[34:35], v[34:35], v[26:27]
	v_pk_mul_f32 v[36:37], v[36:37], v[28:29]
	v_pk_mul_f32 v[38:39], v[38:39], v[30:31]
	v_pk_mul_f32 v[40:41], v[40:41], v[32:33]
	v_pk_mul_f32 v[10:11], v[10:11], v[34:35]
	v_pk_mul_f32 v[12:13], v[12:13], v[36:37]
	v_pk_mul_f32 v[14:15], v[14:15], v[38:39]
	v_pk_mul_f32 v[16:17], v[16:17], v[40:41]
	v_cvt_pk_bf16_f32 v6, v10, v11
	v_cvt_pk_bf16_f32 v7, v12, v13
	v_cvt_pk_bf16_f32 v8, v14, v15
	v_cvt_pk_bf16_f32 v9, v16, v17
	global_store_dwordx4 v[2:3], v[6:9], off
	v_lshl_add_u64 v[2:3], v[2:3], 0, s[40:41]
	v_add_u32_e32 v22, 0x18600, v223
	ds_read_b128 v[18:21], v22
	ds_read_b128 v[22:25], v22 offset:16
	s_waitcnt vmcnt(7)
	v_lshlrev_b32_e32 v26, 16, v104
	v_and_b32_e32 v27, 0xffff0000, v104
	v_lshlrev_b32_e32 v28, 16, v105
	v_and_b32_e32 v29, 0xffff0000, v105
	v_lshlrev_b32_e32 v30, 16, v106
	v_and_b32_e32 v31, 0xffff0000, v106
	v_lshlrev_b32_e32 v32, 16, v107
	v_and_b32_e32 v33, 0xffff0000, v107
	v_mul_f32_e32 v34, 0xbfb8aa3b, v26
	v_mul_f32_e32 v35, 0xbfb8aa3b, v27
	v_mul_f32_e32 v36, 0xbfb8aa3b, v28
	v_mul_f32_e32 v37, 0xbfb8aa3b, v29
	v_mul_f32_e32 v38, 0xbfb8aa3b, v30
	v_mul_f32_e32 v39, 0xbfb8aa3b, v31
	v_mul_f32_e32 v40, 0xbfb8aa3b, v32
	v_mul_f32_e32 v41, 0xbfb8aa3b, v33
	v_exp_f32_e32 v34, v34
	v_exp_f32_e32 v35, v35
	v_exp_f32_e32 v36, v36
	v_exp_f32_e32 v37, v37
	v_exp_f32_e32 v38, v38
	v_exp_f32_e32 v39, v39
	v_exp_f32_e32 v40, v40
	v_exp_f32_e32 v41, v41
	v_add_f32_e32 v34, 1.0, v34
	v_add_f32_e32 v35, 1.0, v35
	v_add_f32_e32 v36, 1.0, v36
	v_add_f32_e32 v37, 1.0, v37
	v_add_f32_e32 v38, 1.0, v38
	v_add_f32_e32 v39, 1.0, v39
	v_add_f32_e32 v40, 1.0, v40
	v_add_f32_e32 v41, 1.0, v41
	v_rcp_f32_e32 v34, v34
	v_rcp_f32_e32 v35, v35
	v_rcp_f32_e32 v36, v36
	v_rcp_f32_e32 v37, v37
	v_rcp_f32_e32 v38, v38
	v_rcp_f32_e32 v39, v39
	v_rcp_f32_e32 v40, v40
	v_rcp_f32_e32 v41, v41
	s_waitcnt lgkmcnt(0)
; #define LAS __attribute__((address_space(3)))
; DI unsigned pk2(float lo, float hi) { f32x2 v = {lo, hi}; return __builtin_bit_cast(unsigned, __builtin_convertvector(v, bf16x2v)); }
; DI float bflo(unsigned u) { return __uint_as_float(u << 16); }
; DI float bfhi(unsigned u) { return __uint_as_float(u & 0xffff0000u); }
; DI float silu_f(float x) { return x * __builtin_amdgcn_rcpf(1.0f + __builtin_amdgcn_exp2f(-1.4426950408889634f * x)); }
; DI void ret_step2(LAS unsigned char* lds, const bf16_t* Z, const bf16_t* SP, bf16_t* MIX, const float* rng, int n, int h, int tid) {
;     ...
;         const int it = k * 512 + tid, tk = it >> 5, c8 = (it & 31) * 8; const size_t token = (size_t)n * 128 + tk;
;         const u32x4 gz = *(const u32x4*)(Z + token * INW + C_RG + h * 256 + c8);
;         const f32x4 g0 = *(const f32x4*)(rng + h * 256 + c8), g1 = *(const f32x4*)(rng + h * 256 + c8 + 4);
;         const f32x4 p0 = *(const LAS f32x4*)(lds + tk * 1040 + c8 * 4), p1 = *(const LAS f32x4*)(lds + tk * 1040 + c8 * 4 + 16);
;         u32x4 o;
;         o.x = pk2(p0[0] * g0[0] * silu_f(bflo(gz.x)), p0[1] * g0[1] * silu_f(bfhi(gz.x))); o.y = pk2(p0[2] * g0[2] * silu_f(bflo(gz.y)), p0[3] * g0[3] * silu_f(bfhi(gz.y)));
;         o.z = pk2(p1[0] * g1[0] * silu_f(bflo(gz.z)), p1[1] * g1[1] * silu_f(bfhi(gz.z))); o.w = pk2(p1[2] * g1[2] * silu_f(bflo(gz.w)), p1[3] * g1[3] * silu_f(bfhi(gz.w)));
;         *(u32x4*)(MIX + token * DM + 1024 + h * 256 + c8) = o;
;     }
;     __syncthreads();
; __global__ void __launch_bounds__(512, 2) fwd_kernel(Args a) {
;     ...
;         for (int u = bx; u < 256; u += G) ret_step2(lds, Z, SP, MIX, rng, u >> 2, u & 3, tid);
	v_pk_mul_f32 v[10:11], v[72:73], v[18:19]
	v_pk_mul_f32 v[12:13], v[74:75], v[20:21]
	v_pk_mul_f32 v[14:15], v[76:77], v[22:23]
	v_pk_mul_f32 v[16:17], v[78:79], v[24:25]
	v_pk_mul_f32 v[34:35], v[34:35], v[26:27]
	v_pk_mul_f32 v[36:37], v[36:37], v[28:29]
	v_pk_mul_f32 v[38:39], v[38:39], v[30:31]
	v_pk_mul_f32 v[40:41], v[40:41], v[32:33]
	v_pk_mul_f32 v[10:11], v[10:11], v[34:35]
	v_pk_mul_f32 v[12:13], v[12:13], v[36:37]
	v_pk_mul_f32 v[14:15], v[14:15], v[38:39]
	v_pk_mul_f32 v[16:17], v[16:17], v[40:41]
	v_cvt_pk_bf16_f32 v6, v10, v11
	v_cvt_pk_bf16_f32 v7, v12, v13
	v_cvt_pk_bf16_f32 v8, v14, v15
	v_cvt_pk_bf16_f32 v9, v16, v17
	global_store_dwordx4 v[2:3], v[6:9], off
	v_lshl_add_u64 v[2:3], v[2:3], 0, s[40:41]
	v_add_u32_e32 v22, 0x1c700, v223
	ds_read_b128 v[18:21], v22
	ds_read_b128 v[22:25], v22 offset:16
	s_waitcnt vmcnt(7)
	v_lshlrev_b32_e32 v26, 16, v108
	v_and_b32_e32 v27, 0xffff0000, v108
	v_lshlrev_b32_e32 v28, 16, v109
	v_and_b32_e32 v29, 0xffff0000, v109
	v_lshlrev_b32_e32 v30, 16, v110
	v_and_b32_e32 v31, 0xffff0000, v110
	v_lshlrev_b32_e32 v32, 16, v111
	v_and_b32_e32 v33, 0xffff0000, v111
	v_mul_f32_e32 v34, 0xbfb8aa3b, v26
	v_mul_f32_e32 v35, 0xbfb8aa3b, v27
	v_mul_f32_e32 v36, 0xbfb8aa3b, v28
	v_mul_f32_e32 v37, 0xbfb8aa3b, v29
	v_mul_f32_e32 v38, 0xbfb8aa3b, v30
	v_mul_f32_e32 v39, 0xbfb8aa3b, v31
	v_mul_f32_e32 v40, 0xbfb8aa3b, v32
	v_mul_f32_e32 v41, 0xbfb8aa3b, v33
	v_exp_f32_e32 v34, v34
	v_exp_f32_e32 v35, v35
	v_exp_f32_e32 v36, v36
	v_exp_f32_e32 v37, v37
	v_exp_f32_e32 v38, v38
	v_exp_f32_e32 v39, v39
	v_exp_f32_e32 v40, v40
	v_exp_f32_e32 v41, v41
	v_add_f32_e32 v34, 1.0, v34
	v_add_f32_e32 v35, 1.0, v35
	v_add_f32_e32 v36, 1.0, v36
	v_add_f32_e32 v37, 1.0, v37
	v_add_f32_e32 v38, 1.0, v38
	v_add_f32_e32 v39, 1.0, v39
	v_add_f32_e32 v40, 1.0, v40
	v_add_f32_e32 v41, 1.0, v41
	v_rcp_f32_e32 v34, v34
	v_rcp_f32_e32 v35, v35
	v_rcp_f32_e32 v36, v36
	v_rcp_f32_e32 v37, v37
	v_rcp_f32_e32 v38, v38
	v_rcp_f32_e32 v39, v39
	v_rcp_f32_e32 v40, v40
	v_rcp_f32_e32 v41, v41
	s_waitcnt lgkmcnt(0)
	v_pk_mul_f32 v[10:11], v[72:73], v[18:19]
	v_pk_mul_f32 v[12:13], v[74:75], v[20:21]
	v_pk_mul_f32 v[14:15], v[76:77], v[22:23]
	v_pk_mul_f32 v[16:17], v[78:79], v[24:25]
	v_pk_mul_f32 v[34:35], v[34:35], v[26:27]
	v_pk_mul_f32 v[36:37], v[36:37], v[28:29]
	v_pk_mul_f32 v[38:39], v[38:39], v[30:31]
	v_pk_mul_f32 v[40:41], v[40:41], v[32:33]
	v_pk_mul_f32 v[10:11], v[10:11], v[34:35]
	v_pk_mul_f32 v[12:13], v[12:13], v[36:37]
	v_pk_mul_f32 v[14:15], v[14:15], v[38:39]
	v_pk_mul_f32 v[16:17], v[16:17], v[40:41]
	v_cvt_pk_bf16_f32 v6, v10, v11
	v_cvt_pk_bf16_f32 v7, v12, v13
	v_cvt_pk_bf16_f32 v8, v14, v15
	v_cvt_pk_bf16_f32 v9, v16, v17
	global_store_dwordx4 v[2:3], v[6:9], off
	s_add_i32 s76, s76, s64
	s_add_i32 s75, s75, s64
	v_lshl_add_u64 v[164:165], v[164:165], 0, s[48:49]
	s_cmpk_gt_i32 s76, 0xff
	v_lshl_add_u64 v[166:167], v[166:167], 0, s[48:49]
	s_barrier
	s_cbranch_scc0 .LBB0_406
; DI void attn_prompt_unit(LAS unsigned char* lds, const bf16_t* Z, bf16_t* MIX, const float* gq, const float* gk, const float* sinks, float* o_k, float* o_v, int nb, int kh, int hf, int tid) {
;     LAS unsigned char* Kn = lds; LAS unsigned char* Vt = lds + 256 * 144;
;     const int lane = tid & 63, wid = tid >> 6, r = lane & 31, hh = lane >> 5;
;     {
;         const int row = tid >> 1, half = tid & 1; const int tok = (nb - 1) * 128 + row;
;         u32x4 v[4];
; #pragma unroll
;         for (int c = 0; c < 4; ++c) v[c] = (u32x4){0u, 0u, 0u, 0u};
;         if (tok >= 0) {
; #pragma unroll
;             for (int c = 0; c < 4; ++c) v[c] = *(const u32x4*)(Z + (size_t)tok * INW + C_AK + kh * 64 + half * 32 + c * 8);
;         }
;         float f[32]; float ss = 0.f;
; #pragma unroll
;         for (int c = 0; c < 4; ++c)
; #pragma unroll
;             for (int e = 0; e < 4; ++e) { f[c * 8 + 2 * e] = bflo(v[c][e]); f[c * 8 + 2 * e + 1] = bfhi(v[c][e]); }
; #pragma unroll
;         for (int e = 0; e < 32; ++e) ss += f[e] * f[e];
;         ss += __shfl_xor(ss, 1);
;         const float rstd = rsqrtf(ss * (1.0f / 64.0f) + EPS);
; #pragma unroll
;         for (int c = 0; c < 8; ++c) { const f32x4 g = *(const f32x4*)(gk + half * 32 + c * 4);
; #pragma unroll
;             for (int e = 0; e < 4; ++e) f[c * 4 + e] *= rstd * g[e]; }
; #pragma unroll
;         for (int c = 0; c < 4; ++c) { u32x4 w; w.x = pk2(f[c * 8], f[c * 8 + 1]); w.y = pk2(f[c * 8 + 2], f[c * 8 + 3]); w.z = pk2(f[c * 8 + 4], f[c * 8 + 5]); w.w = pk2(f[c * 8 + 6], f[c * 8 + 7]);
;             *(LAS u32x4*)(Kn + row * 144 + half * 64 + c * 16) = w; }
;         if (nb == 63 && hf == 0 && row >= 128) { float* o = o_k + ((size_t)(row - 128) * 2 + kh) * 64 + half * 32;
; #pragma unroll
;             for (int c = 0; c < 8; ++c) *(f32x4*)(o + c * 4) = (f32x4){f[c * 4], f[c * 4 + 1], f[c * 4 + 2], f[c * 4 + 3]}; }
;     }
; #pragma unroll
;     for (int k = 0; k < 2; ++k) {
;         const int it = k * 512 + tid, kpl = it & 15, dgl = (it >> 4) & 3, rest = it >> 6, dg = dgl + 4 * (rest & 1), kp = kpl + 16 * (rest >> 1);
;         const int tok0 = (nb - 1) * 128 + 2 * kp;
;         u32x4 a = {0u, 0u, 0u, 0u}, b = {0u, 0u, 0u, 0u};
;         if (tok0 >= 0) { const bf16_t* p = Z + (size_t)tok0 * INW + C_AV + kh * 64 + dg * 8; a = *(const u32x4*)p; b = *(const u32x4*)(p + INW); }
; #pragma unroll
	s_movk_i32 s0, 0xff
	v_cmp_lt_u32_e64 s[0:1], s0, v253
	v_lshrrev_b32_e32 v122, 1, v253
	v_mov_b32_e32 v93, 0
	v_writelane_b32 v254, s0, 23
	v_add_u32_e32 v92, 0xffffff80, v122
	v_and_b32_e32 v94, 56, v122
	v_writelane_b32 v254, s1, 24
	v_lshlrev_b64 v[2:3], 9, v[92:93]
	v_readlane_b32 s76, v254, 7
	v_readlane_b32 s90, v254, 21
	v_readlane_b32 s91, v254, 22
	v_lshlrev_b32_e32 v92, 2, v94
	s_mov_b64 s[0:1], 0x4110000
	v_lshl_add_u64 v[4:5], s[90:91], 0, v[92:93]
	v_and_b32_e32 v8, 15, v253
	v_lshl_add_u64 v[96:97], v[4:5], 0, s[0:1]
	v_lshrrev_b32_e32 v4, 3, v253
	s_movk_i32 s0, 0x70
	v_and_or_b32 v4, v4, s0, v8
	s_movk_i32 s0, 0x1ff
	v_cmp_lt_u32_e64 s[0:1], s0, v253
	v_readlane_b32 s77, v254, 8
	v_readlane_b32 s78, v254, 9
	v_readlane_b32 s79, v254, 10
	v_readlane_b32 s80, v254, 11
	v_readlane_b32 s81, v254, 12
	v_readlane_b32 s82, v254, 13
	v_readlane_b32 s83, v254, 14
	v_readlane_b32 s84, v254, 15
	v_readlane_b32 s85, v254, 16
	v_readlane_b32 s86, v254, 17
	v_readlane_b32 s87, v254, 18
	v_readlane_b32 s88, v254, 19
	v_readlane_b32 s89, v254, 20
	v_writelane_b32 v254, s0, 37
	v_lshlrev_b32_e32 v92, 10, v4
	v_lshlrev_b32_e32 v123, 1, v4
	v_writelane_b32 v254, s1, 38
	s_mov_b32 s0, 0xffff0000
	s_mov_b32 s1, -1
	v_lshl_add_u32 v5, v4, 2, 0
	v_lshl_add_u64 v[98:99], v[92:93], 0, s[0:1]
	v_lshrrev_b32_e32 v4, 3, v200
	s_movk_i32 s0, 0xf0
	v_and_or_b32 v4, v4, s0, v8
	v_or_b32_e32 v8, 1, v211
	v_cmp_lt_u32_e64 s[0:1], v8, v154
	v_lshlrev_b32_e32 v124, 1, v4
	v_add_u32_e32 v92, 0xffffff80, v124
	v_writelane_b32 v254, s0, 35
	v_lshlrev_b64 v[100:101], 9, v[92:93]
	v_lshlrev_b32_e32 v92, 2, v156
	v_writelane_b32 v254, s1, 36
	v_cmp_lt_u32_e64 s[0:1], v215, v154
	v_and_b32_e32 v1, 1, v253
	v_lshl_add_u64 v[104:105], s[58:59], 0, v[92:93]
	v_writelane_b32 v254, s0, 33
	v_lshlrev_b32_e32 v92, 1, v211
	v_xor_b32_e32 v10, 1, v217
	v_writelane_b32 v254, s1, 34
	v_cmp_lt_u32_e64 s[0:1], v214, v154
	s_movk_i32 s33, 0x90
	v_lshl_add_u64 v[2:3], s[90:91], 0, v[2:3]
	v_writelane_b32 v254, s0, 39
	v_lshl_add_u64 v[106:107], s[56:57], 0, v[92:93]
	v_cmp_lt_i32_e32 vcc, v10, v64
	v_writelane_b32 v254, s1, 40
	v_cmp_lt_u32_e64 s[0:1], v213, v154
	v_lshlrev_b32_e32 v92, 7, v1
	v_lshlrev_b32_e32 v0, 5, v1
	v_writelane_b32 v254, s0, 43
	v_mad_u32_u24 v6, v122, s33, 0
	v_lshlrev_b32_e32 v7, 6, v1
	v_writelane_b32 v254, s1, 44
	v_cmp_lt_u32_e64 s[0:1], v212, v154
	v_mul_u32_u24_e32 v9, 0x208, v94
	v_lshl_add_u32 v4, v4, 2, 0
	v_writelane_b32 v254, s0, 45
	v_mov_b32_e32 v163, v93
	v_mul_u32_u24_e32 v8, 0x208, v154
	v_writelane_b32 v254, s1, 46
	v_cmp_lt_u32_e64 s[0:1], v210, v154
	v_cndmask_b32_e32 v10, v217, v10, vcc
	v_lshl_add_u64 v[2:3], v[2:3], 0, v[92:93]
	v_writelane_b32 v254, s0, 47
	s_mov_b32 s51, 0
	v_and_b32_e32 v125, 2, v199
	v_writelane_b32 v254, s1, 48
	v_cmp_lt_u32_e64 s[0:1], v209, v154
	v_lshl_add_u64 v[102:103], s[54:55], 0, v[162:163]
	v_lshlrev_b32_e32 v126, 2, v10
	v_writelane_b32 v254, s0, 49
	v_lshl_add_u64 v[108:109], s[76:77], 0, v[92:93]
	v_add3_u32 v127, 0, v156, v8
	v_writelane_b32 v254, s1, 50
	v_cmp_lt_u32_e64 s[0:1], v208, v154
	s_movk_i32 s68, 0x2a00
	v_lshlrev_b32_e32 v112, 1, v0
	v_writelane_b32 v254, s0, 51
	v_mov_b32_e32 v128, 0x358637bd
	s_mov_b32 s69, 0x800000
	v_writelane_b32 v254, s1, 52
	v_cmp_lt_u32_e64 s[0:1], v207, v154
	v_add_u32_e32 v129, v6, v7
	s_mov_b32 s70, 0xffff
	v_writelane_b32 v254, s0, 53
	v_add_u32_e32 v130, v5, v9
	v_add_u32_e32 v131, v4, v9
	v_writelane_b32 v254, s1, 54
	v_cmp_lt_u32_e64 s[0:1], v206, v154
	v_mov_b32_e32 v132, 0xf149f2ca
	s_mov_b32 s71, s92
	v_writelane_b32 v254, s0, 55
	s_nop 1
	v_writelane_b32 v254, s1, 56
	v_cmp_lt_u32_e64 s[0:1], v205, v154
	s_nop 1
	v_writelane_b32 v254, s0, 57
	s_nop 1
	v_writelane_b32 v254, s1, 58
	v_cmp_lt_u32_e64 s[0:1], v204, v154
	s_nop 1
	v_writelane_b32 v254, s0, 59
	s_nop 1
	v_writelane_b32 v254, s1, 60
	v_cmp_lt_u32_e64 s[0:1], v203, v154
	s_nop 1
	v_writelane_b32 v254, s0, 61
	s_nop 1
	v_writelane_b32 v254, s1, 62
	v_cmp_lt_u32_e64 s[0:1], v202, v154
	s_nop 1
	v_writelane_b32 v254, s0, 63
	s_nop 1
	v_writelane_b32 v255, s1, 0
	v_cmp_lt_u32_e64 s[0:1], v201, v154
	s_nop 1
	v_writelane_b32 v255, s0, 1
	s_nop 1
	v_writelane_b32 v255, s1, 2
	s_mov_b64 s[0:1], 0x4100000
	v_lshl_add_u64 v[110:111], v[2:3], 0, s[0:1]

; #define PG8_WAIT_V(n) asm volatile("s_waitcnt vmcnt(" #n ")" ::: "memory")
; #define PG8_BAR __builtin_amdgcn_s_barrier()
; template <class Epi, class Sched, bool ALIGN_EPI = false, bool SP2 = false>
; __device__ __forceinline__ void gemm_phase(PG8_LAS unsigned char* lds, const Gemm g, const Sched& S, const Epi& E) {
;     ...
;     PG8_WAIT_V(0);
;     if constexpr (!ALIGN_EPI) { if (wr == 0) PG8_BAR; }
;     PG8_BAR;
; __global__ void __launch_bounds__(512, 2) fwd_kernel(Args a) {
;     ...
;         const SkOut SE{x_s, out + O_Y + (size_t)LP * DM, XG + (size_t)LP * DM};
;         for (int u = bx; u < 4 * (DM / 32); u += G) skinny_unit<1>(lds, MIX + (size_t)LP * DM, WOUT, DM, u >> 2, 0, (u & 3) * 32, SE, tid);
.LBB0_549:
	s_waitcnt lgkmcnt(0)
	s_mov_b64 exec, -1
	v_readlane_b32 s16, v254, 15
	v_readlane_b32 s17, v254, 16
	v_readlane_b32 s18, v254, 17
	v_readlane_b32 s19, v254, 18
	v_readlane_b32 s20, v254, 19
	v_readlane_b32 s21, v254, 20
	v_readlane_b32 s22, v254, 21
	v_readlane_b32 s23, v254, 22
	v_and_b32_e32 v20, 15, v253
	v_bfe_u32 v21, v253, 4, 2
	v_lshrrev_b32_e32 v22, 6, v253
	v_lshlrev_b32_e32 v16, 12, v20
	v_lshl_add_u32 v16, v22, 9, v16
	v_lshl_add_u32 v16, v21, 4, v16
	v_readfirstlane_b32 s1, v22
	v_lshlrev_b32_e32 v17, 12, v22
	v_lshl_add_u32 v17, v21, 9, v17
	v_lshl_add_u32 v17, v20, 2, v17
	v_lshrrev_b32_e32 v23, 3, v253
	v_and_b32_e32 v24, 7, v253
	v_lshlrev_b32_e32 v18, 7, v23
	v_lshl_add_u32 v18, v24, 4, v18
	v_lshlrev_b32_e32 v19, 13, v23
	v_lshl_add_u32 v19, v24, 4, v19
	v_lshrrev_b32_e32 v148, 4, v23
	v_lshlrev_b32_e32 v148, 10, v148
	v_lshrrev_b32_e32 v149, 1, v24
	v_lshl_add_u32 v148, v149, 8, v148
	v_and_b32_e32 v149, 15, v23
	v_lshl_add_u32 v148, v149, 4, v148
	v_and_b32_e32 v149, 1, v24
	v_lshl_add_u32 v148, v149, 3, v148
	s_add_u32 s4, s60, 0xa000000
	s_addc_u32 s5, s61, 0
	s_add_u32 s8, s60, 0x1700000
	s_addc_u32 s9, s61, 0
	s_mov_b32 s0, s92

; #define LAS __attribute__((address_space(3)))
; template <int MT, class Epi>
; DI void skinny_unit(LAS unsigned char* lds, const bf16_t* A, const bf16_t* Wt, int K, int cgi, int k0, int row0, const Epi& E, int tid) {
;     ...
;     LAS float* red = (LAS float*)lds;
; #pragma unroll
;     for (int mt = 0; mt < NMT; ++mt)
; #pragma unroll
;         for (int nt = 0; nt < 2; ++nt)
; #pragma unroll
;             for (int j = 0; j < 4; ++j) red[(wid * NR + mt * 16 + 4 * fq + j) * 32 + nt * 16 + fr] = acc[mt][nt][j];
;     __syncthreads();
;     if (MT == 4) {
;         const int row = tid >> 2, c8 = (tid & 3) * 8;
;         f32x4 sa = {0.f, 0.f, 0.f, 0.f}, sb = {0.f, 0.f, 0.f, 0.f};
; #pragma unroll
;         for (int w = 0; w < 8; ++w) { sa += *(const LAS f32x4*)(red + (w * NR + row) * 32 + c8); sb += *(const LAS f32x4*)(red + (w * NR + row) * 32 + c8 + 4); }
;         E(row0 + row, c0 + c8, sa); E(row0 + row, c0 + c8 + 4, sb);
;     } else if (tid < 8 * NR) {
;         const int row = tid >> 3, c4 = (tid & 7) * 4;
;         f32x4 sa = {0.f, 0.f, 0.f, 0.f};
; #pragma unroll
;         for (int w = 0; w < 8; ++w) sa += *(const LAS f32x4*)(red + (w * NR + row) * 32 + c4);
;         E(row0 + row, c0 + c4, sa);
;     }
.Lsk5_nox:
	v_add_u32_e32 v149, 0x800, v17
	s_nop 7
	s_nop 3
	s_barrier
	ds_write2_b32 v17, v0, v4 offset1:16
	ds_write2_b32 v17, v1, v5 offset0:32 offset1:48
	ds_write2_b32 v17, v2, v6 offset0:64 offset1:80
	ds_write2_b32 v17, v3, v7 offset0:96 offset1:112
	ds_write2_b32 v149, v8, v12 offset1:16
	ds_write2_b32 v149, v9, v13 offset0:32 offset1:48
	ds_write2_b32 v149, v10, v14 offset0:64 offset1:80
	ds_write2_b32 v149, v11, v15 offset0:96 offset1:112
	s_waitcnt lgkmcnt(0)
	s_barrier
	s_cmp_lt_u32 s1, 4
	s_cbranch_scc0 .Lsk5_skip
	ds_read_b128 v[20:23], v18 offset:0
	ds_read_b128 v[24:27], v18 offset:4096
	ds_read_b128 v[28:31], v18 offset:8192
	ds_read_b128 v[32:35], v18 offset:12288
	ds_read_b128 v[36:39], v18 offset:16384
	ds_read_b128 v[40:43], v18 offset:20480
	ds_read_b128 v[44:47], v18 offset:24576
	ds_read_b128 v[48:51], v18 offset:28672
	s_waitcnt lgkmcnt(6)
	v_pk_add_f32 v[20:21], v[20:21], v[24:25]
	v_pk_add_f32 v[22:23], v[22:23], v[26:27]
	s_waitcnt lgkmcnt(5)
	v_pk_add_f32 v[20:21], v[20:21], v[28:29]
	v_pk_add_f32 v[22:23], v[22:23], v[30:31]
	s_waitcnt lgkmcnt(4)
	v_pk_add_f32 v[20:21], v[20:21], v[32:33]
	v_pk_add_f32 v[22:23], v[22:23], v[34:35]
	s_waitcnt lgkmcnt(3)
	v_pk_add_f32 v[20:21], v[20:21], v[36:37]
	v_pk_add_f32 v[22:23], v[22:23], v[38:39]
	s_waitcnt lgkmcnt(2)
	v_pk_add_f32 v[20:21], v[20:21], v[40:41]
	v_pk_add_f32 v[22:23], v[22:23], v[42:43]
	s_waitcnt lgkmcnt(1)
	v_pk_add_f32 v[20:21], v[20:21], v[44:45]
	v_pk_add_f32 v[22:23], v[22:23], v[46:47]
	s_waitcnt lgkmcnt(0)
	v_pk_add_f32 v[20:21], v[20:21], v[48:49]
	v_pk_add_f32 v[22:23], v[22:23], v[50:51]
	s_waitcnt vmcnt(0)
	v_pk_add_f32 v[20:21], v[20:21], v[84:85]
	v_pk_add_f32 v[22:23], v[22:23], v[86:87]
	global_store_dwordx4 v19, v[20:23], s[28:29]
	v_cvt_pk_bf16_f32 v24, v20, v21
	v_cvt_pk_bf16_f32 v25, v22, v23
	global_store_dwordx2 v148, v[24:25], s[30:31]

; #define LAS __attribute__((address_space(3)))
; #define PG8_WAIT_V(n) asm volatile("s_waitcnt vmcnt(" #n ")" ::: "memory")
; #define PG8_BAR __builtin_amdgcn_s_barrier()
; #define SK_LOAD(buf, c) do { _Pragma("unroll") for (int nt = 0; nt < 2; ++nt) fb[buf][nt] = *(const bf16x8*)(pb + nt * rs + 32 * (c)); \
;         _Pragma("unroll") for (int mt = 0; mt < NMT; ++mt) fa[buf][mt] = *(const bf16x8*)(pa + mt * rs + 32 * (c)); } while (0)
; #define SK_MMA(buf) do { _Pragma("unroll") for (int mt = 0; mt < NMT; ++mt) _Pragma("unroll") for (int nt = 0; nt < 2; ++nt) \
;         acc[mt][nt] = __builtin_amdgcn_mfma_f32_16x16x32_bf16(fa[buf][mt], fb[buf][nt], acc[mt][nt], 0, 0, 0); } while (0)
; template <class Epi, class Sched, bool ALIGN_EPI = false, bool SP2 = false>
; __device__ __forceinline__ void gemm_phase(PG8_LAS unsigned char* lds, const Gemm g, const Sched& S, const Epi& E) {
;     ...
;     PG8_WAIT_V(0);
;     if constexpr (!ALIGN_EPI) { if (wr == 0) PG8_BAR; }
;     PG8_BAR;
; template <int MT, class Epi>
; DI void skinny_unit(LAS unsigned char* lds, const bf16_t* A, const bf16_t* Wt, int K, int cgi, int k0, int row0, const Epi& E, int tid) {
;     const int lane = tid & 63, wid = tid >> 6, fr = lane & 15, fq = lane >> 4;
;     const int c0 = cgi * 32;
;     constexpr int NMT = 2 * MT;
;     const bf16_t* pa = A + (size_t)(row0 + fr) * K + k0 + wid * 256 + 8 * fq;
;     const bf16_t* pb = Wt + (size_t)(c0 + fr) * K + k0 + wid * 256 + 8 * fq;
;     const size_t rs = (size_t)16 * K;
;     f32x4 acc[NMT][2];
; #pragma unroll
;     for (int i = 0; i < NMT; ++i) { acc[i][0] = (f32x4){0.f, 0.f, 0.f, 0.f}; acc[i][1] = (f32x4){0.f, 0.f, 0.f, 0.f}; }
;     bf16x8 fb[3][2], fa[3][NMT];
;     ...
;     SK_LOAD(0, 0); SK_LOAD(1, 1);
;     SK_LOAD(2, 2); SK_MMA(0);
;     SK_LOAD(0, 3); SK_MMA(1);
;     SK_LOAD(1, 4); SK_MMA(2);
;     SK_LOAD(2, 5); SK_MMA(0);
;     SK_LOAD(0, 6); SK_MMA(1);
;     SK_LOAD(1, 7); SK_MMA(2);
;     SK_MMA(0); SK_MMA(1);
.LBB0_635:
.LBB0_636:
	s_cmpk_gt_i32 s92, 0xff
	s_cbranch_scc1 .LBB0_639
	s_waitcnt lgkmcnt(0)
	s_mov_b64 exec, -1
	v_and_b32_e32 v70, 15, v253
	v_bfe_u32 v71, v253, 4, 2
	v_lshrrev_b32_e32 v72, 6, v253
	v_mul_u32_u24_e32 v64, 0x1000, v70
	v_lshl_add_u32 v64, v72, 9, v64
	v_lshl_add_u32 v64, v71, 4, v64
	v_readfirstlane_b32 s1, v72
	v_and_b32_e32 v69, 63, v253
	v_lshlrev_b32_e32 v69, 4, v69
	v_mul_u32_u24_e32 v65, 0x4000, v72
	v_lshl_add_u32 v65, v71, 9, v65
	v_lshl_add_u32 v65, v70, 2, v65
	v_lshrrev_b32_e32 v73, 2, v253
	v_and_b32_e32 v74, 3, v253
	v_lshlrev_b32_e32 v66, 7, v73
	v_lshl_add_u32 v66, v74, 5, v66
	v_add_u32_e32 v67, 0x10000, v66
	v_and_b32_e32 v68, 15, v73
	v_lshl_add_u32 v68, v74, 4, v68
	v_lshlrev_b32_e32 v68, 4, v68
	v_lshl_add_u32 v68, v72, 10, v68
	s_add_u32 s2, s60, 0x7f00000
	s_addc_u32 s3, s61, 0
	s_add_u32 s6, s60, 0x1f00000
	s_addc_u32 s7, s61, 0
	s_lshl_b32 s1, s1, 16
	s_add_u32 s2, s2, s1
	s_addc_u32 s3, s3, 0
	s_mov_b32 s0, s92
.Lsk6_loop:
	s_mov_b64 s[14:15], s[2:3]
	s_lshl_b32 s8, s0, 17
	s_add_u32 s8, s6, s8
	s_addc_u32 s9, s7, 0
	s_add_u32 s10, s8, 0x10000
	s_addc_u32 s11, s9, 0
	s_lshl_b32 s12, s0, 13
	s_add_u32 s12, s12, 0x12400000
	s_add_u32 s12, s60, s12
	s_addc_u32 s13, s61, 0
	global_load_dwordx4 v[108:111], v64, s[8:9] offset:0 nt
	global_load_dwordx4 v[148:151], v64, s[8:9] offset:64 nt
	global_load_dwordx4 v[112:115], v64, s[10:11] offset:0 nt
	global_load_dwordx4 v[152:155], v64, s[10:11] offset:64 nt
	global_load_dwordx4 v[76:79], v69, s[14:15] offset:0
	global_load_dwordx4 v[80:83], v69, s[14:15] offset:1024
	global_load_dwordx4 v[84:87], v69, s[14:15] offset:2048
	global_load_dwordx4 v[88:91], v69, s[14:15] offset:3072
	s_add_u32 s14, s14, 0x1000
	s_addc_u32 s15, s15, 0
	global_load_dwordx4 v[92:95], v69, s[14:15] offset:0
	global_load_dwordx4 v[96:99], v69, s[14:15] offset:1024
	global_load_dwordx4 v[100:103], v69, s[14:15] offset:2048
	global_load_dwordx4 v[104:107], v69, s[14:15] offset:3072
	s_add_u32 s14, s14, 0x1000
	s_addc_u32 s15, s15, 0
	global_load_dwordx4 v[116:119], v69, s[14:15] offset:0
	global_load_dwordx4 v[120:123], v69, s[14:15] offset:1024
	global_load_dwordx4 v[124:127], v69, s[14:15] offset:2048
	global_load_dwordx4 v[128:131], v69, s[14:15] offset:3072
	s_add_u32 s14, s14, 0x1000
	s_addc_u32 s15, s15, 0
	global_load_dwordx4 v[132:135], v69, s[14:15] offset:0
	global_load_dwordx4 v[136:139], v69, s[14:15] offset:1024
	global_load_dwordx4 v[140:143], v69, s[14:15] offset:2048
	global_load_dwordx4 v[144:147], v69, s[14:15] offset:3072
	s_add_u32 s14, s14, 0x1000
	s_addc_u32 s15, s15, 0
	global_load_dwordx4 v[188:191], v64, s[8:9] offset:128 nt
	global_load_dwordx4 v[228:231], v64, s[8:9] offset:192 nt
	global_load_dwordx4 v[192:195], v64, s[10:11] offset:128 nt
	global_load_dwordx4 v[232:235], v64, s[10:11] offset:192 nt
	global_load_dwordx4 v[156:159], v69, s[14:15] offset:0
	global_load_dwordx4 v[160:163], v69, s[14:15] offset:1024
	global_load_dwordx4 v[164:167], v69, s[14:15] offset:2048
	global_load_dwordx4 v[168:171], v69, s[14:15] offset:3072
	s_add_u32 s14, s14, 0x1000
	s_addc_u32 s15, s15, 0
	global_load_dwordx4 v[172:175], v69, s[14:15] offset:0
	global_load_dwordx4 v[176:179], v69, s[14:15] offset:1024
	global_load_dwordx4 v[180:183], v69, s[14:15] offset:2048
	global_load_dwordx4 v[184:187], v69, s[14:15] offset:3072
	s_add_u32 s14, s14, 0x1000
	s_addc_u32 s15, s15, 0
	global_load_dwordx4 v[196:199], v69, s[14:15] offset:0
	global_load_dwordx4 v[200:203], v69, s[14:15] offset:1024
	global_load_dwordx4 v[204:207], v69, s[14:15] offset:2048
	global_load_dwordx4 v[208:211], v69, s[14:15] offset:3072
	s_add_u32 s14, s14, 0x1000
	s_addc_u32 s15, s15, 0
	global_load_dwordx4 v[212:215], v69, s[14:15] offset:0
	global_load_dwordx4 v[216:219], v69, s[14:15] offset:1024
	global_load_dwordx4 v[220:223], v69, s[14:15] offset:2048
	global_load_dwordx4 v[224:227], v69, s[14:15] offset:3072
	s_add_u32 s14, s14, 0x1000
	s_addc_u32 s15, s15, 0
	s_waitcnt vmcnt(20)
	v_mfma_f32_16x16x32_bf16 v[0:3], v[76:79], v[108:111], 0
	v_mfma_f32_16x16x32_bf16 v[4:7], v[76:79], v[112:115], 0
	v_mfma_f32_16x16x32_bf16 v[8:11], v[80:83], v[108:111], 0
	v_mfma_f32_16x16x32_bf16 v[12:15], v[80:83], v[112:115], 0
	v_mfma_f32_16x16x32_bf16 v[16:19], v[84:87], v[108:111], 0
	v_mfma_f32_16x16x32_bf16 v[20:23], v[84:87], v[112:115], 0
	v_mfma_f32_16x16x32_bf16 v[24:27], v[88:91], v[108:111], 0
	v_mfma_f32_16x16x32_bf16 v[28:31], v[88:91], v[112:115], 0
	v_mfma_f32_16x16x32_bf16 v[32:35], v[92:95], v[108:111], 0
	v_mfma_f32_16x16x32_bf16 v[36:39], v[92:95], v[112:115], 0
	v_mfma_f32_16x16x32_bf16 v[40:43], v[96:99], v[108:111], 0
	v_mfma_f32_16x16x32_bf16 v[44:47], v[96:99], v[112:115], 0
	v_mfma_f32_16x16x32_bf16 v[48:51], v[100:103], v[108:111], 0
	v_mfma_f32_16x16x32_bf16 v[52:55], v[100:103], v[112:115], 0
	v_mfma_f32_16x16x32_bf16 v[56:59], v[104:107], v[108:111], 0
	v_mfma_f32_16x16x32_bf16 v[60:63], v[104:107], v[112:115], 0
	v_mfma_f32_16x16x32_bf16 v[0:3], v[116:119], v[148:151], v[0:3]
	v_mfma_f32_16x16x32_bf16 v[4:7], v[116:119], v[152:155], v[4:7]
	v_mfma_f32_16x16x32_bf16 v[8:11], v[120:123], v[148:151], v[8:11]
	v_mfma_f32_16x16x32_bf16 v[12:15], v[120:123], v[152:155], v[12:15]
	v_mfma_f32_16x16x32_bf16 v[16:19], v[124:127], v[148:151], v[16:19]
	v_mfma_f32_16x16x32_bf16 v[20:23], v[124:127], v[152:155], v[20:23]
	v_mfma_f32_16x16x32_bf16 v[24:27], v[128:131], v[148:151], v[24:27]
	v_mfma_f32_16x16x32_bf16 v[28:31], v[128:131], v[152:155], v[28:31]
	v_mfma_f32_16x16x32_bf16 v[32:35], v[132:135], v[148:151], v[32:35]
	v_mfma_f32_16x16x32_bf16 v[36:39], v[132:135], v[152:155], v[36:39]
; #define SK_LOAD(buf, c) do { _Pragma("unroll") for (int nt = 0; nt < 2; ++nt) fb[buf][nt] = *(const bf16x8*)(pb + nt * rs + 32 * (c)); \
;         _Pragma("unroll") for (int mt = 0; mt < NMT; ++mt) fa[buf][mt] = *(const bf16x8*)(pa + mt * rs + 32 * (c)); } while (0)
; #define SK_MMA(buf) do { _Pragma("unroll") for (int mt = 0; mt < NMT; ++mt) _Pragma("unroll") for (int nt = 0; nt < 2; ++nt) \
;         acc[mt][nt] = __builtin_amdgcn_mfma_f32_16x16x32_bf16(fa[buf][mt], fb[buf][nt], acc[mt][nt], 0, 0, 0); } while (0)
; template <int MT, class Epi>
; DI void skinny_unit(LAS unsigned char* lds, const bf16_t* A, const bf16_t* Wt, int K, int cgi, int k0, int row0, const Epi& E, int tid) {
;     ...
;     SK_LOAD(0, 0); SK_LOAD(1, 1);
;     SK_LOAD(2, 2); SK_MMA(0);
;     SK_LOAD(0, 3); SK_MMA(1);
;     SK_LOAD(1, 4); SK_MMA(2);
;     SK_LOAD(2, 5); SK_MMA(0);
;     SK_LOAD(0, 6); SK_MMA(1);
;     SK_LOAD(1, 7); SK_MMA(2);
	v_mfma_f32_16x16x32_bf16 v[40:43], v[136:139], v[148:151], v[40:43]
	v_mfma_f32_16x16x32_bf16 v[44:47], v[136:139], v[152:155], v[44:47]
	v_mfma_f32_16x16x32_bf16 v[48:51], v[140:143], v[148:151], v[48:51]
	v_mfma_f32_16x16x32_bf16 v[52:55], v[140:143], v[152:155], v[52:55]
	v_mfma_f32_16x16x32_bf16 v[56:59], v[144:147], v[148:151], v[56:59]
	v_mfma_f32_16x16x32_bf16 v[60:63], v[144:147], v[152:155], v[60:63]
	global_load_dwordx4 v[108:111], v64, s[8:9] offset:256 nt
	global_load_dwordx4 v[148:151], v64, s[8:9] offset:320 nt
	global_load_dwordx4 v[112:115], v64, s[10:11] offset:256 nt
	global_load_dwordx4 v[152:155], v64, s[10:11] offset:320 nt
	global_load_dwordx4 v[76:79], v69, s[14:15] offset:0
	global_load_dwordx4 v[80:83], v69, s[14:15] offset:1024
	global_load_dwordx4 v[84:87], v69, s[14:15] offset:2048
	global_load_dwordx4 v[88:91], v69, s[14:15] offset:3072
	s_add_u32 s14, s14, 0x1000
	s_addc_u32 s15, s15, 0
	global_load_dwordx4 v[92:95], v69, s[14:15] offset:0
	global_load_dwordx4 v[96:99], v69, s[14:15] offset:1024
	global_load_dwordx4 v[100:103], v69, s[14:15] offset:2048
	global_load_dwordx4 v[104:107], v69, s[14:15] offset:3072
	s_add_u32 s14, s14, 0x1000
	s_addc_u32 s15, s15, 0
	global_load_dwordx4 v[116:119], v69, s[14:15] offset:0
	global_load_dwordx4 v[120:123], v69, s[14:15] offset:1024
	global_load_dwordx4 v[124:127], v69, s[14:15] offset:2048
	global_load_dwordx4 v[128:131], v69, s[14:15] offset:3072
	s_add_u32 s14, s14, 0x1000
	s_addc_u32 s15, s15, 0
	global_load_dwordx4 v[132:135], v69, s[14:15] offset:0
	global_load_dwordx4 v[136:139], v69, s[14:15] offset:1024
	global_load_dwordx4 v[140:143], v69, s[14:15] offset:2048
	global_load_dwordx4 v[144:147], v69, s[14:15] offset:3072
	s_add_u32 s14, s14, 0x1000
	s_addc_u32 s15, s15, 0
	s_waitcnt vmcnt(20)
	v_mfma_f32_16x16x32_bf16 v[0:3], v[156:159], v[188:191], v[0:3]
	v_mfma_f32_16x16x32_bf16 v[4:7], v[156:159], v[192:195], v[4:7]
	v_mfma_f32_16x16x32_bf16 v[8:11], v[160:163], v[188:191], v[8:11]
	v_mfma_f32_16x16x32_bf16 v[12:15], v[160:163], v[192:195], v[12:15]
	v_mfma_f32_16x16x32_bf16 v[16:19], v[164:167], v[188:191], v[16:19]
	v_mfma_f32_16x16x32_bf16 v[20:23], v[164:167], v[192:195], v[20:23]
	v_mfma_f32_16x16x32_bf16 v[24:27], v[168:171], v[188:191], v[24:27]
	v_mfma_f32_16x16x32_bf16 v[28:31], v[168:171], v[192:195], v[28:31]
	v_mfma_f32_16x16x32_bf16 v[32:35], v[172:175], v[188:191], v[32:35]
	v_mfma_f32_16x16x32_bf16 v[36:39], v[172:175], v[192:195], v[36:39]
	v_mfma_f32_16x16x32_bf16 v[40:43], v[176:179], v[188:191], v[40:43]
	v_mfma_f32_16x16x32_bf16 v[44:47], v[176:179], v[192:195], v[44:47]
	v_mfma_f32_16x16x32_bf16 v[48:51], v[180:183], v[188:191], v[48:51]
	v_mfma_f32_16x16x32_bf16 v[52:55], v[180:183], v[192:195], v[52:55]
	v_mfma_f32_16x16x32_bf16 v[56:59], v[184:187], v[188:191], v[56:59]
	v_mfma_f32_16x16x32_bf16 v[60:63], v[184:187], v[192:195], v[60:63]
	v_mfma_f32_16x16x32_bf16 v[0:3], v[196:199], v[228:231], v[0:3]
	v_mfma_f32_16x16x32_bf16 v[4:7], v[196:199], v[232:235], v[4:7]
	v_mfma_f32_16x16x32_bf16 v[8:11], v[200:203], v[228:231], v[8:11]
	v_mfma_f32_16x16x32_bf16 v[12:15], v[200:203], v[232:235], v[12:15]
	v_mfma_f32_16x16x32_bf16 v[16:19], v[204:207], v[228:231], v[16:19]
	v_mfma_f32_16x16x32_bf16 v[20:23], v[204:207], v[232:235], v[20:23]
	v_mfma_f32_16x16x32_bf16 v[24:27], v[208:211], v[228:231], v[24:27]
	v_mfma_f32_16x16x32_bf16 v[28:31], v[208:211], v[232:235], v[28:31]
	v_mfma_f32_16x16x32_bf16 v[32:35], v[212:215], v[228:231], v[32:35]
	v_mfma_f32_16x16x32_bf16 v[36:39], v[212:215], v[232:235], v[36:39]
	v_mfma_f32_16x16x32_bf16 v[40:43], v[216:219], v[228:231], v[40:43]
	v_mfma_f32_16x16x32_bf16 v[44:47], v[216:219], v[232:235], v[44:47]
	v_mfma_f32_16x16x32_bf16 v[48:51], v[220:223], v[228:231], v[48:51]
	v_mfma_f32_16x16x32_bf16 v[52:55], v[220:223], v[232:235], v[52:55]
	v_mfma_f32_16x16x32_bf16 v[56:59], v[224:227], v[228:231], v[56:59]
	v_mfma_f32_16x16x32_bf16 v[60:63], v[224:227], v[232:235], v[60:63]
	global_load_dwordx4 v[188:191], v64, s[8:9] offset:384 nt
	global_load_dwordx4 v[228:231], v64, s[8:9] offset:448 nt
	global_load_dwordx4 v[192:195], v64, s[10:11] offset:384 nt
	global_load_dwordx4 v[232:235], v64, s[10:11] offset:448 nt
	global_load_dwordx4 v[156:159], v69, s[14:15] offset:0
	global_load_dwordx4 v[160:163], v69, s[14:15] offset:1024
	global_load_dwordx4 v[164:167], v69, s[14:15] offset:2048
	global_load_dwordx4 v[168:171], v69, s[14:15] offset:3072
	s_add_u32 s14, s14, 0x1000
	s_addc_u32 s15, s15, 0
	global_load_dwordx4 v[172:175], v69, s[14:15] offset:0
	global_load_dwordx4 v[176:179], v69, s[14:15] offset:1024
	global_load_dwordx4 v[180:183], v69, s[14:15] offset:2048
	global_load_dwordx4 v[184:187], v69, s[14:15] offset:3072
	s_add_u32 s14, s14, 0x1000
	s_addc_u32 s15, s15, 0
	global_load_dwordx4 v[196:199], v69, s[14:15] offset:0
	global_load_dwordx4 v[200:203], v69, s[14:15] offset:1024
	global_load_dwordx4 v[204:207], v69, s[14:15] offset:2048
	global_load_dwordx4 v[208:211], v69, s[14:15] offset:3072
	s_add_u32 s14, s14, 0x1000
	s_addc_u32 s15, s15, 0
	global_load_dwordx4 v[212:215], v69, s[14:15] offset:0
	global_load_dwordx4 v[216:219], v69, s[14:15] offset:1024
	global_load_dwordx4 v[220:223], v69, s[14:15] offset:2048
	global_load_dwordx4 v[224:227], v69, s[14:15] offset:3072
	s_waitcnt vmcnt(20)
; #define LAS __attribute__((address_space(3)))
; #define SK_LOAD(buf, c) do { _Pragma("unroll") for (int nt = 0; nt < 2; ++nt) fb[buf][nt] = *(const bf16x8*)(pb + nt * rs + 32 * (c)); \
;         _Pragma("unroll") for (int mt = 0; mt < NMT; ++mt) fa[buf][mt] = *(const bf16x8*)(pa + mt * rs + 32 * (c)); } while (0)
; #define SK_MMA(buf) do { _Pragma("unroll") for (int mt = 0; mt < NMT; ++mt) _Pragma("unroll") for (int nt = 0; nt < 2; ++nt) \
;         acc[mt][nt] = __builtin_amdgcn_mfma_f32_16x16x32_bf16(fa[buf][mt], fb[buf][nt], acc[mt][nt], 0, 0, 0); } while (0)
; template <int MT, class Epi>
; DI void skinny_unit(LAS unsigned char* lds, const bf16_t* A, const bf16_t* Wt, int K, int cgi, int k0, int row0, const Epi& E, int tid) {
;     ...
;     SK_LOAD(1, 7); SK_MMA(2);
;     SK_MMA(0); SK_MMA(1);
;     ...
;     constexpr int NR = 32 * MT;
;     LAS float* red = (LAS float*)lds;
; #pragma unroll
;     for (int mt = 0; mt < NMT; ++mt)
; #pragma unroll
;         for (int nt = 0; nt < 2; ++nt)
; #pragma unroll
;             for (int j = 0; j < 4; ++j) red[(wid * NR + mt * 16 + 4 * fq + j) * 32 + nt * 16 + fr] = acc[mt][nt][j];
	v_mfma_f32_16x16x32_bf16 v[0:3], v[76:79], v[108:111], v[0:3]
	v_mfma_f32_16x16x32_bf16 v[4:7], v[76:79], v[112:115], v[4:7]
	v_mfma_f32_16x16x32_bf16 v[8:11], v[80:83], v[108:111], v[8:11]
	v_mfma_f32_16x16x32_bf16 v[12:15], v[80:83], v[112:115], v[12:15]
	v_mfma_f32_16x16x32_bf16 v[16:19], v[84:87], v[108:111], v[16:19]
	v_mfma_f32_16x16x32_bf16 v[20:23], v[84:87], v[112:115], v[20:23]
	v_mfma_f32_16x16x32_bf16 v[24:27], v[88:91], v[108:111], v[24:27]
	v_mfma_f32_16x16x32_bf16 v[28:31], v[88:91], v[112:115], v[28:31]
	v_mfma_f32_16x16x32_bf16 v[32:35], v[92:95], v[108:111], v[32:35]
	v_mfma_f32_16x16x32_bf16 v[36:39], v[92:95], v[112:115], v[36:39]
	v_mfma_f32_16x16x32_bf16 v[40:43], v[96:99], v[108:111], v[40:43]
	v_mfma_f32_16x16x32_bf16 v[44:47], v[96:99], v[112:115], v[44:47]
	v_mfma_f32_16x16x32_bf16 v[48:51], v[100:103], v[108:111], v[48:51]
	v_mfma_f32_16x16x32_bf16 v[52:55], v[100:103], v[112:115], v[52:55]
	v_mfma_f32_16x16x32_bf16 v[56:59], v[104:107], v[108:111], v[56:59]
	v_mfma_f32_16x16x32_bf16 v[60:63], v[104:107], v[112:115], v[60:63]
	v_mfma_f32_16x16x32_bf16 v[0:3], v[116:119], v[148:151], v[0:3]
	v_mfma_f32_16x16x32_bf16 v[4:7], v[116:119], v[152:155], v[4:7]
	v_mfma_f32_16x16x32_bf16 v[8:11], v[120:123], v[148:151], v[8:11]
	v_mfma_f32_16x16x32_bf16 v[12:15], v[120:123], v[152:155], v[12:15]
	v_mfma_f32_16x16x32_bf16 v[16:19], v[124:127], v[148:151], v[16:19]
	v_mfma_f32_16x16x32_bf16 v[20:23], v[124:127], v[152:155], v[20:23]
	v_mfma_f32_16x16x32_bf16 v[24:27], v[128:131], v[148:151], v[24:27]
	v_mfma_f32_16x16x32_bf16 v[28:31], v[128:131], v[152:155], v[28:31]
	v_mfma_f32_16x16x32_bf16 v[32:35], v[132:135], v[148:151], v[32:35]
	v_mfma_f32_16x16x32_bf16 v[36:39], v[132:135], v[152:155], v[36:39]
	v_mfma_f32_16x16x32_bf16 v[40:43], v[136:139], v[148:151], v[40:43]
	v_mfma_f32_16x16x32_bf16 v[44:47], v[136:139], v[152:155], v[44:47]
	v_mfma_f32_16x16x32_bf16 v[48:51], v[140:143], v[148:151], v[48:51]
	v_mfma_f32_16x16x32_bf16 v[52:55], v[140:143], v[152:155], v[52:55]
	v_mfma_f32_16x16x32_bf16 v[56:59], v[144:147], v[148:151], v[56:59]
	v_mfma_f32_16x16x32_bf16 v[60:63], v[144:147], v[152:155], v[60:63]
	s_waitcnt vmcnt(0)
	v_mfma_f32_16x16x32_bf16 v[0:3], v[156:159], v[188:191], v[0:3]
	v_mfma_f32_16x16x32_bf16 v[4:7], v[156:159], v[192:195], v[4:7]
	v_mfma_f32_16x16x32_bf16 v[8:11], v[160:163], v[188:191], v[8:11]
	v_mfma_f32_16x16x32_bf16 v[12:15], v[160:163], v[192:195], v[12:15]
	v_mfma_f32_16x16x32_bf16 v[16:19], v[164:167], v[188:191], v[16:19]
	v_mfma_f32_16x16x32_bf16 v[20:23], v[164:167], v[192:195], v[20:23]
	v_mfma_f32_16x16x32_bf16 v[24:27], v[168:171], v[188:191], v[24:27]
	v_mfma_f32_16x16x32_bf16 v[28:31], v[168:171], v[192:195], v[28:31]
	v_mfma_f32_16x16x32_bf16 v[32:35], v[172:175], v[188:191], v[32:35]
	v_mfma_f32_16x16x32_bf16 v[36:39], v[172:175], v[192:195], v[36:39]
	v_mfma_f32_16x16x32_bf16 v[40:43], v[176:179], v[188:191], v[40:43]
	v_mfma_f32_16x16x32_bf16 v[44:47], v[176:179], v[192:195], v[44:47]
	v_mfma_f32_16x16x32_bf16 v[48:51], v[180:183], v[188:191], v[48:51]
	v_mfma_f32_16x16x32_bf16 v[52:55], v[180:183], v[192:195], v[52:55]
	v_mfma_f32_16x16x32_bf16 v[56:59], v[184:187], v[188:191], v[56:59]
	v_mfma_f32_16x16x32_bf16 v[60:63], v[184:187], v[192:195], v[60:63]
	v_mfma_f32_16x16x32_bf16 v[0:3], v[196:199], v[228:231], v[0:3]
	v_mfma_f32_16x16x32_bf16 v[4:7], v[196:199], v[232:235], v[4:7]
	v_mfma_f32_16x16x32_bf16 v[8:11], v[200:203], v[228:231], v[8:11]
	v_mfma_f32_16x16x32_bf16 v[12:15], v[200:203], v[232:235], v[12:15]
	v_mfma_f32_16x16x32_bf16 v[16:19], v[204:207], v[228:231], v[16:19]
	v_mfma_f32_16x16x32_bf16 v[20:23], v[204:207], v[232:235], v[20:23]
	v_mfma_f32_16x16x32_bf16 v[24:27], v[208:211], v[228:231], v[24:27]
	v_mfma_f32_16x16x32_bf16 v[28:31], v[208:211], v[232:235], v[28:31]
	v_mfma_f32_16x16x32_bf16 v[32:35], v[212:215], v[228:231], v[32:35]
	v_mfma_f32_16x16x32_bf16 v[36:39], v[212:215], v[232:235], v[36:39]
	v_mfma_f32_16x16x32_bf16 v[40:43], v[216:219], v[228:231], v[40:43]
	v_mfma_f32_16x16x32_bf16 v[44:47], v[216:219], v[232:235], v[44:47]
	v_mfma_f32_16x16x32_bf16 v[48:51], v[220:223], v[228:231], v[48:51]
	v_mfma_f32_16x16x32_bf16 v[52:55], v[220:223], v[232:235], v[52:55]
	v_mfma_f32_16x16x32_bf16 v[56:59], v[224:227], v[228:231], v[56:59]
	v_mfma_f32_16x16x32_bf16 v[60:63], v[224:227], v[232:235], v[60:63]
	v_add_u32_e32 v77, 0x800, v65
	v_add_u32_e32 v78, 0x1000, v65
	v_add_u32_e32 v79, 0x1800, v65
	v_add_u32_e32 v80, 0x2000, v65
	v_add_u32_e32 v81, 0x2800, v65
	v_add_u32_e32 v82, 0x3000, v65
	v_add_u32_e32 v83, 0x3800, v65
	s_nop 7
	s_nop 3
	s_barrier
; #define LAS __attribute__((address_space(3)))
; template <int MT, class Epi>
; DI void skinny_unit(LAS unsigned char* lds, const bf16_t* A, const bf16_t* Wt, int K, int cgi, int k0, int row0, const Epi& E, int tid) {
;     ...
;             for (int j = 0; j < 4; ++j) red[(wid * NR + mt * 16 + 4 * fq + j) * 32 + nt * 16 + fr] = acc[mt][nt][j];
;     __syncthreads();
;     if (MT == 4) {
;         const int row = tid >> 2, c8 = (tid & 3) * 8;
;         f32x4 sa = {0.f, 0.f, 0.f, 0.f}, sb = {0.f, 0.f, 0.f, 0.f};
; #pragma unroll
;         for (int w = 0; w < 8; ++w) { sa += *(const LAS f32x4*)(red + (w * NR + row) * 32 + c8); sb += *(const LAS f32x4*)(red + (w * NR + row) * 32 + c8 + 4); }
;         E(row0 + row, c0 + c8, sa); E(row0 + row, c0 + c8 + 4, sb);
	ds_write2_b32 v65, v0, v4 offset1:16
	ds_write2_b32 v65, v1, v5 offset0:32 offset1:48
	ds_write2_b32 v65, v2, v6 offset0:64 offset1:80
	ds_write2_b32 v65, v3, v7 offset0:96 offset1:112
	ds_write2_b32 v77, v8, v12 offset1:16
	ds_write2_b32 v77, v9, v13 offset0:32 offset1:48
	ds_write2_b32 v77, v10, v14 offset0:64 offset1:80
	ds_write2_b32 v77, v11, v15 offset0:96 offset1:112
	ds_write2_b32 v78, v16, v20 offset1:16
	ds_write2_b32 v78, v17, v21 offset0:32 offset1:48
	ds_write2_b32 v78, v18, v22 offset0:64 offset1:80
	ds_write2_b32 v78, v19, v23 offset0:96 offset1:112
	ds_write2_b32 v79, v24, v28 offset1:16
	ds_write2_b32 v79, v25, v29 offset0:32 offset1:48
	ds_write2_b32 v79, v26, v30 offset0:64 offset1:80
	ds_write2_b32 v79, v27, v31 offset0:96 offset1:112
	ds_write2_b32 v80, v32, v36 offset1:16
	ds_write2_b32 v80, v33, v37 offset0:32 offset1:48
	ds_write2_b32 v80, v34, v38 offset0:64 offset1:80
	ds_write2_b32 v80, v35, v39 offset0:96 offset1:112
	ds_write2_b32 v81, v40, v44 offset1:16
	ds_write2_b32 v81, v41, v45 offset0:32 offset1:48
	ds_write2_b32 v81, v42, v46 offset0:64 offset1:80
	ds_write2_b32 v81, v43, v47 offset0:96 offset1:112
	ds_write2_b32 v82, v48, v52 offset1:16
	ds_write2_b32 v82, v49, v53 offset0:32 offset1:48
	ds_write2_b32 v82, v50, v54 offset0:64 offset1:80
	ds_write2_b32 v82, v51, v55 offset0:96 offset1:112
	ds_write2_b32 v83, v56, v60 offset1:16
	ds_write2_b32 v83, v57, v61 offset0:32 offset1:48
	ds_write2_b32 v83, v58, v62 offset0:64 offset1:80
	ds_write2_b32 v83, v59, v63 offset0:96 offset1:112
	s_waitcnt lgkmcnt(0)
	s_barrier
	ds_read_b128 v[76:79], v66 offset:0
	ds_read_b128 v[80:83], v66 offset:16
	ds_read_b128 v[84:87], v66 offset:16384
	ds_read_b128 v[88:91], v66 offset:16400
	ds_read_b128 v[92:95], v66 offset:32768
	ds_read_b128 v[96:99], v66 offset:32784
	ds_read_b128 v[100:103], v66 offset:49152
	ds_read_b128 v[104:107], v66 offset:49168
	ds_read_b128 v[108:111], v67 offset:0
	ds_read_b128 v[112:115], v67 offset:16
	ds_read_b128 v[116:119], v67 offset:16384
	ds_read_b128 v[120:123], v67 offset:16400
	ds_read_b128 v[124:127], v67 offset:32768
	ds_read_b128 v[128:131], v67 offset:32784
	ds_read_b128 v[132:135], v67 offset:49152
	ds_read_b128 v[136:139], v67 offset:49168
	s_waitcnt lgkmcnt(12)
	v_pk_add_f32 v[76:77], v[76:77], v[84:85]
	v_pk_add_f32 v[78:79], v[78:79], v[86:87]
	v_pk_add_f32 v[80:81], v[80:81], v[88:89]
	v_pk_add_f32 v[82:83], v[82:83], v[90:91]
	s_waitcnt lgkmcnt(10)
	v_pk_add_f32 v[76:77], v[76:77], v[92:93]
	v_pk_add_f32 v[78:79], v[78:79], v[94:95]
	v_pk_add_f32 v[80:81], v[80:81], v[96:97]
	v_pk_add_f32 v[82:83], v[82:83], v[98:99]
	s_waitcnt lgkmcnt(8)
	v_pk_add_f32 v[76:77], v[76:77], v[100:101]
	v_pk_add_f32 v[78:79], v[78:79], v[102:103]
	v_pk_add_f32 v[80:81], v[80:81], v[104:105]
	v_pk_add_f32 v[82:83], v[82:83], v[106:107]
	s_waitcnt lgkmcnt(6)
	v_pk_add_f32 v[76:77], v[76:77], v[108:109]
	v_pk_add_f32 v[78:79], v[78:79], v[110:111]
	v_pk_add_f32 v[80:81], v[80:81], v[112:113]
	v_pk_add_f32 v[82:83], v[82:83], v[114:115]
	s_waitcnt lgkmcnt(4)
	v_pk_add_f32 v[76:77], v[76:77], v[116:117]
	v_pk_add_f32 v[78:79], v[78:79], v[118:119]
	v_pk_add_f32 v[80:81], v[80:81], v[120:121]
	v_pk_add_f32 v[82:83], v[82:83], v[122:123]
	s_waitcnt lgkmcnt(2)
	v_pk_add_f32 v[76:77], v[76:77], v[124:125]
	v_pk_add_f32 v[78:79], v[78:79], v[126:127]
	v_pk_add_f32 v[80:81], v[80:81], v[128:129]
	v_pk_add_f32 v[82:83], v[82:83], v[130:131]
	s_waitcnt lgkmcnt(0)
	v_pk_add_f32 v[76:77], v[76:77], v[132:133]
	v_pk_add_f32 v[78:79], v[78:79], v[134:135]
	v_pk_add_f32 v[80:81], v[80:81], v[136:137]
	v_pk_add_f32 v[82:83], v[82:83], v[138:139]
	v_max_f32_e32 v76, 0, v76
	v_max_f32_e32 v77, 0, v77
	v_max_f32_e32 v78, 0, v78
	v_max_f32_e32 v79, 0, v79
	v_max_f32_e32 v80, 0, v80
	v_max_f32_e32 v81, 0, v81
	v_max_f32_e32 v82, 0, v82
	v_max_f32_e32 v83, 0, v83
	v_pk_mul_f32 v[76:77], v[76:77], v[76:77]
	v_pk_mul_f32 v[78:79], v[78:79], v[78:79]
	v_pk_mul_f32 v[80:81], v[80:81], v[80:81]
	v_pk_mul_f32 v[82:83], v[82:83], v[82:83]
	v_cvt_pk_bf16_f32 v84, v76, v77
	v_cvt_pk_bf16_f32 v85, v78, v79
	v_cvt_pk_bf16_f32 v86, v80, v81
	v_cvt_pk_bf16_f32 v87, v82, v83
	global_store_dwordx4 v68, v[84:87], s[12:13]
	s_add_i32 s0, s0, s64
	s_cmpk_lt_i32 s0, 0x100
	s_barrier
	s_cbranch_scc1 .Lsk6_loop
